# k16 plus loop-edge rotation (7.11): K-loop counter/address scalar work moved from the load-segment head into the last compute segment, 3 StaticOrder GEMM loops
# speedup vs baseline: 1.0038x; 1.0038x over previous
;     __device__ bool next(int i, Unit& u) const { if (i >= 2) return false; const int x = c & 7, j = c >> 3; u.pm = 32 * i + 4 * x + (j & 3); u.pn = j >> 2; return true; }
; #define PG8_STAGE(bufoff, gbase, voff) do { _Pragma("unroll") for (int _i = 0; _i < 2; ++_i) \
;         __builtin_amdgcn_global_load_lds((const unsigned*)((const char*)(gbase) + (voff)[_i]), (LAS unsigned*)(lds + (bufoff) + ldsw + _i * 8192), 16, 0, 0); } while (0)
; #define PG8_LDA(dst, b, h) do { _Pragma("unroll") for (int m = 0; m < 4; ++m) _Pragma("unroll") for (int k = 0; k < 2; ++k) dst[m][k] = *(const LAS bf16x8*)(lds + PG8_SA(b, h) + aoff + m * 2048 + k * 1024); } while (0)
; #define PG8_LDB(dst, b, h) do { _Pragma("unroll") for (int n = 0; n < 2; ++n) _Pragma("unroll") for (int k = 0; k < 2; ++k) dst[n][k] = *(const LAS bf16x8*)(lds + PG8_SB(b, h) + boff + n * 2048 + k * 1024); } while (0)
; #define PG8_WAIT_V(n) asm volatile("s_waitcnt vmcnt(" #n ")" ::: "memory")
; #define PG8_WAIT_L(n) asm volatile("s_waitcnt lgkmcnt(" #n ")" ::: "memory")
; #define PG8_BAR __builtin_amdgcn_s_barrier()
; template <class Epi, class Sched, bool ALIGN_EPI = true>
; __device__ __forceinline__ void gemm_phase(LAS unsigned char* lds, const Gemm g, const Sched& S, const Epi& E) {
;     ...
;         const bool has_next = S.next(ui + 1, nxt);
;         const char* nA = has_next ? (const char*)g.A + ((size_t)nxt.pm * BM * g.lda + (size_t)nxt.pn * g.a_pn_off) * 2 : cA; const char* nB = has_next ? (const char*)g.Bt + (size_t)nxt.pn * BM * g.ldb * 2 : cB;
;         for (int t = 0; t < nt; t += 2) {
;             const bool last = (t == nt - 2);
;             const char* a1 = cA + (size_t)(t + 1) * kstep;
;             const char* a2 = last ? nA : cA + (size_t)(t + 2) * kstep; const char* b2 = last ? nB : cB + (size_t)(t + 2) * kstep;
;             const char* a3 = a2 + kstep; const char* b3 = b2 + kstep;
;             PG8_LDB(B0, 0, 0); PG8_LDB(B1, 0, 1); PG8_SCHED; PG8_LDA(At, 0, 0); PG8_STAGE(PG8_SA(1, 1), a1 + hA, voffA);
;             PG8_WAIT_V(8); PG8_WAIT_L(0); PG8_BAR; PG8_MMA(0, 0, At, B0); PG8_MMA(0, 1, At, B1); PG8_BAR; PG8_SCHED;
;             PG8_LDA(At, 0, 1); PG8_STAGE(PG8_SB(0, 0), b2, voffB); PG8_STAGE(PG8_SB(0, 1), b2 + hB, voffB); PG8_STAGE(PG8_SA(0, 0), a2, voffA);
;             PG8_WAIT_V(8); PG8_WAIT_L(0); PG8_BAR; PG8_MMA(1, 0, At, B0); PG8_MMA(1, 1, At, B1); PG8_BAR; PG8_SCHED;
.LBB0_76:
	s_ashr_i32 s15, s14, 31
	s_lshl_b64 s[18:19], s[14:15], 20
	s_add_u32 s38, s46, s18
	s_addc_u32 s39, s47, s19
	s_and_b64 s[18:19], s[4:5], exec
	s_cselect_b32 s15, s39, s7
	s_cselect_b32 s17, s38, s6
	s_ashr_i32 s13, s12, 31
	s_lshl_b64 s[18:19], s[12:13], 20
	s_add_u32 s40, s53, s18
	s_addc_u32 s41, s58, s19
	s_and_b64 s[18:19], s[4:5], exec
	s_cselect_b32 s13, s41, s43
	s_cselect_b32 s18, s40, s42
	s_add_u32 s6, s6, 0x80080
	s_addc_u32 s7, s7, 0
	s_add_u32 s19, s42, 0x100
	s_addc_u32 s24, s43, 0
	s_mov_b32 s25, -2
	s_add_u32 s26, s6, 0xfff80080
	s_addc_u32 s27, s7, -1
	s_add_i32 s30, 0, 0x10000
	s_cmp_eq_u32 s25, 28
	s_cselect_b32 s45, s15, s27
	s_cselect_b32 s44, s17, s26
	s_cselect_b32 s43, s13, s24
	s_cselect_b32 s42, s18, s19
	s_add_i32 s31, 0, 0x14000
	v_add_u32_e32 v144, s30, v166
	v_add_u32_e32 v156, s31, v166
	ds_read_b128 v[132:135], v144
	ds_read_b128 v[136:139], v144 offset:1024
	ds_read_b128 v[140:143], v144 offset:2048
	ds_read_b128 v[144:147], v144 offset:3072
	ds_read_b128 v[170:173], v156
	ds_read_b128 v[174:177], v156 offset:1024
	ds_read_b128 v[178:181], v156 offset:2048
	ds_read_b128 v[182:185], v156 offset:3072
	v_lshl_add_u64 v[156:157], s[6:7], 0, v[152:153]
	s_add_i32 m0, s60, 0xc000
	ds_read_b128 v[186:189], v168
	ds_read_b128 v[190:193], v168 offset:1024
	ds_read_b128 v[194:197], v168 offset:2048
	ds_read_b128 v[204:207], v168 offset:3072
	ds_read_b128 v[208:211], v168 offset:4096
	ds_read_b128 v[212:215], v168 offset:5120
	ds_read_b128 v[216:219], v168 offset:6144
	ds_read_b128 v[220:223], v168 offset:7168
	global_load_lds_dwordx4 v[156:157], off
	v_lshl_add_u64 v[156:157], s[6:7], 0, v[154:155]
	s_add_i32 m0, s60, 0xe000
	s_nop 0
	global_load_lds_dwordx4 v[156:157], off
	s_waitcnt vmcnt(8)
	s_waitcnt lgkmcnt(0)
	s_barrier
	s_setprio 1
	s_waitcnt lgkmcnt(0)
	v_mfma_f32_16x16x32_bf16 v[128:131], v[132:135], v[186:189], 0
	v_mfma_f32_16x16x32_bf16 v[128:131], v[136:139], v[190:193], v[128:131]
	v_mfma_f32_16x16x32_bf16 v[124:127], v[140:143], v[186:189], 0
	v_mfma_f32_16x16x32_bf16 v[124:127], v[144:147], v[190:193], v[124:127]
	v_mfma_f32_16x16x32_bf16 v[116:119], v[132:135], v[194:197], 0
	v_mfma_f32_16x16x32_bf16 v[116:119], v[136:139], v[204:207], v[116:119]
	v_mfma_f32_16x16x32_bf16 v[112:115], v[140:143], v[194:197], 0
	v_mfma_f32_16x16x32_bf16 v[112:115], v[144:147], v[204:207], v[112:115]
	v_mfma_f32_16x16x32_bf16 v[104:107], v[132:135], v[208:211], 0
	v_mfma_f32_16x16x32_bf16 v[104:107], v[136:139], v[212:215], v[104:107]
	v_mfma_f32_16x16x32_bf16 v[96:99], v[140:143], v[208:211], 0
	v_mfma_f32_16x16x32_bf16 v[96:99], v[144:147], v[212:215], v[96:99]
	v_mfma_f32_16x16x32_bf16 v[88:91], v[132:135], v[216:219], 0
	v_mfma_f32_16x16x32_bf16 v[88:91], v[136:139], v[220:223], v[88:91]
	v_mfma_f32_16x16x32_bf16 v[80:83], v[140:143], v[216:219], 0
	v_mfma_f32_16x16x32_bf16 v[80:83], v[144:147], v[220:223], v[80:83]
	s_setprio 0
	s_setprio 1
	v_mfma_f32_16x16x32_bf16 v[120:123], v[170:173], v[186:189], 0
	v_mfma_f32_16x16x32_bf16 v[120:123], v[174:177], v[190:193], v[120:123]
	v_mfma_f32_16x16x32_bf16 v[108:111], v[178:181], v[186:189], 0
	v_mfma_f32_16x16x32_bf16 v[108:111], v[182:185], v[190:193], v[108:111]
	v_mfma_f32_16x16x32_bf16 v[100:103], v[170:173], v[194:197], 0
	v_mfma_f32_16x16x32_bf16 v[100:103], v[174:177], v[204:207], v[100:103]
	v_mfma_f32_16x16x32_bf16 v[92:95], v[178:181], v[194:197], 0
	v_mfma_f32_16x16x32_bf16 v[92:95], v[182:185], v[204:207], v[92:95]
	v_mfma_f32_16x16x32_bf16 v[84:87], v[170:173], v[208:211], 0
	v_mfma_f32_16x16x32_bf16 v[84:87], v[174:177], v[212:215], v[84:87]
	v_mfma_f32_16x16x32_bf16 v[76:79], v[178:181], v[208:211], 0
	v_mfma_f32_16x16x32_bf16 v[76:79], v[182:185], v[212:215], v[76:79]
	v_mfma_f32_16x16x32_bf16 v[72:75], v[170:173], v[216:219], 0
	v_mfma_f32_16x16x32_bf16 v[72:75], v[174:177], v[220:223], v[72:75]
	s_setprio 2
	s_barrier
	v_mfma_f32_16x16x32_bf16 v[68:71], v[178:181], v[216:219], 0
	v_mfma_f32_16x16x32_bf16 v[68:71], v[182:185], v[220:223], v[68:71]
	s_setprio 0
	s_add_i32 s26, s30, s59
	v_lshl_add_u64 v[156:157], s[42:43], 0, v[2:3]
	s_mov_b32 m0, s26
	ds_read_b128 v[186:189], v168 offset:16384
	ds_read_b128 v[190:193], v168 offset:17408
	ds_read_b128 v[194:197], v168 offset:18432
	ds_read_b128 v[204:207], v168 offset:19456
	ds_read_b128 v[208:211], v168 offset:20480
	ds_read_b128 v[212:215], v168 offset:21504
	ds_read_b128 v[216:219], v168 offset:22528
	ds_read_b128 v[220:223], v168 offset:23552
	global_load_lds_dwordx4 v[156:157], off
	s_add_i32 m0, s26, 0x2000
	s_add_u32 s26, s42, 0x80000
	v_lshl_add_u64 v[164:165], s[42:43], 0, v[0:1]
	s_addc_u32 s27, s43, 0
	s_add_i32 s30, s31, s59
	global_load_lds_dwordx4 v[164:165], off
	v_lshl_add_u64 v[224:225], s[26:27], 0, v[2:3]
	s_mov_b32 m0, s30
	v_lshl_add_u64 v[226:227], s[44:45], 0, v[148:149]
	global_load_lds_dwordx4 v[224:225], off
	v_lshl_add_u64 v[224:225], s[26:27], 0, v[0:1]
	s_add_i32 m0, s30, 0x2000
	s_nop 0
	global_load_lds_dwordx4 v[224:225], off
	v_lshl_add_u64 v[224:225], s[44:45], 0, v[150:151]
	s_mov_b32 m0, s60
	s_nop 0
	global_load_lds_dwordx4 v[224:225], off
	s_mov_b32 m0, s61
	s_nop 0
	global_load_lds_dwordx4 v[226:227], off
	s_waitcnt vmcnt(8)
	s_waitcnt lgkmcnt(0)
	s_barrier
; #define PG8_STAGE(bufoff, gbase, voff) do { _Pragma("unroll") for (int _i = 0; _i < 2; ++_i) \
;         __builtin_amdgcn_global_load_lds((const unsigned*)((const char*)(gbase) + (voff)[_i]), (LAS unsigned*)(lds + (bufoff) + ldsw + _i * 8192), 16, 0, 0); } while (0)
; #define PG8_LDA(dst, b, h) do { _Pragma("unroll") for (int m = 0; m < 4; ++m) _Pragma("unroll") for (int k = 0; k < 2; ++k) dst[m][k] = *(const LAS bf16x8*)(lds + PG8_SA(b, h) + aoff + m * 2048 + k * 1024); } while (0)
; #define PG8_LDB(dst, b, h) do { _Pragma("unroll") for (int n = 0; n < 2; ++n) _Pragma("unroll") for (int k = 0; k < 2; ++k) dst[n][k] = *(const LAS bf16x8*)(lds + PG8_SB(b, h) + boff + n * 2048 + k * 1024); } while (0)
; #define PG8_MMA(ai, bj, At, Bt) do { __builtin_amdgcn_s_setprio(1); _Pragma("unroll") for (int m = 0; m < 4; ++m) _Pragma("unroll") for (int n = 0; n < 2; ++n) _Pragma("unroll") for (int k = 0; k < 2; ++k) \
;         acc[ai][bj][m][n] = __builtin_amdgcn_mfma_f32_16x16x32_bf16(Bt[n][k], At[m][k], acc[ai][bj][m][n], 0, 0, 0); __builtin_amdgcn_s_setprio(0); } while (0)
; #define PG8_WAIT_V(n) asm volatile("s_waitcnt vmcnt(" #n ")" ::: "memory")
; #define PG8_WAIT_L(n) asm volatile("s_waitcnt lgkmcnt(" #n ")" ::: "memory")
; #define PG8_BAR __builtin_amdgcn_s_barrier()
; #define PG8_SCHED __builtin_amdgcn_sched_barrier(0)
; template <class Epi, class Sched, bool ALIGN_EPI = true>
; __device__ __forceinline__ void gemm_phase(LAS unsigned char* lds, const Gemm g, const Sched& S, const Epi& E) {
;     ...
;             PG8_WAIT_V(8); PG8_WAIT_L(0); PG8_BAR; PG8_MMA(1, 0, At, B0); PG8_MMA(1, 1, At, B1); PG8_BAR; PG8_SCHED;
;             PG8_LDB(B0, 1, 0); PG8_LDB(B1, 1, 1); PG8_SCHED; PG8_LDA(At, 1, 0); PG8_STAGE(PG8_SA(0, 1), a2 + hA, voffA);
;             PG8_WAIT_V(8); PG8_WAIT_L(0); PG8_BAR; PG8_MMA(0, 0, At, B0); PG8_MMA(0, 1, At, B1); PG8_BAR; PG8_SCHED;
	s_setprio 1
	s_waitcnt lgkmcnt(0)
	v_mfma_f32_16x16x32_bf16 v[64:67], v[132:135], v[186:189], 0
	v_mfma_f32_16x16x32_bf16 v[64:67], v[136:139], v[190:193], v[64:67]
	v_mfma_f32_16x16x32_bf16 v[60:63], v[140:143], v[186:189], 0
	v_mfma_f32_16x16x32_bf16 v[60:63], v[144:147], v[190:193], v[60:63]
	v_mfma_f32_16x16x32_bf16 v[56:59], v[132:135], v[194:197], 0
	v_mfma_f32_16x16x32_bf16 v[56:59], v[136:139], v[204:207], v[56:59]
	v_mfma_f32_16x16x32_bf16 v[48:51], v[140:143], v[194:197], 0
	v_mfma_f32_16x16x32_bf16 v[48:51], v[144:147], v[204:207], v[48:51]
	v_mfma_f32_16x16x32_bf16 v[40:43], v[132:135], v[208:211], 0
	v_mfma_f32_16x16x32_bf16 v[40:43], v[136:139], v[212:215], v[40:43]
	v_mfma_f32_16x16x32_bf16 v[32:35], v[140:143], v[208:211], 0
	v_mfma_f32_16x16x32_bf16 v[32:35], v[144:147], v[212:215], v[32:35]
	v_mfma_f32_16x16x32_bf16 v[24:27], v[132:135], v[216:219], 0
	v_mfma_f32_16x16x32_bf16 v[24:27], v[136:139], v[220:223], v[24:27]
	v_mfma_f32_16x16x32_bf16 v[16:19], v[140:143], v[216:219], 0
	v_mfma_f32_16x16x32_bf16 v[16:19], v[144:147], v[220:223], v[16:19]
	s_setprio 0
	s_setprio 1
	v_mfma_f32_16x16x32_bf16 v[52:55], v[170:173], v[186:189], 0
	v_mfma_f32_16x16x32_bf16 v[52:55], v[174:177], v[190:193], v[52:55]
	v_mfma_f32_16x16x32_bf16 v[44:47], v[178:181], v[186:189], 0
	v_mfma_f32_16x16x32_bf16 v[44:47], v[182:185], v[190:193], v[44:47]
	v_mfma_f32_16x16x32_bf16 v[36:39], v[170:173], v[194:197], 0
	v_mfma_f32_16x16x32_bf16 v[36:39], v[174:177], v[204:207], v[36:39]
	v_mfma_f32_16x16x32_bf16 v[28:31], v[178:181], v[194:197], 0
	v_mfma_f32_16x16x32_bf16 v[28:31], v[182:185], v[204:207], v[28:31]
	v_mfma_f32_16x16x32_bf16 v[20:23], v[170:173], v[208:211], 0
	v_mfma_f32_16x16x32_bf16 v[20:23], v[174:177], v[212:215], v[20:23]
	v_mfma_f32_16x16x32_bf16 v[12:15], v[178:181], v[208:211], 0
	v_mfma_f32_16x16x32_bf16 v[12:15], v[182:185], v[212:215], v[12:15]
	v_mfma_f32_16x16x32_bf16 v[8:11], v[170:173], v[216:219], 0
	v_mfma_f32_16x16x32_bf16 v[8:11], v[174:177], v[220:223], v[8:11]
	s_setprio 2
	s_barrier
	v_mfma_f32_16x16x32_bf16 v[4:7], v[178:181], v[216:219], 0
	v_mfma_f32_16x16x32_bf16 v[4:7], v[182:185], v[220:223], v[4:7]
	s_setprio 0
	s_add_i32 s30, 0, 0x18000
	s_add_i32 s31, 0, 0x1c000
	v_add_u32_e32 v144, s30, v166
	v_add_u32_e32 v160, s31, v166
	ds_read_b128 v[132:135], v144
	ds_read_b128 v[136:139], v144 offset:1024
	ds_read_b128 v[140:143], v144 offset:2048
	ds_read_b128 v[144:147], v144 offset:3072
	ds_read_b128 v[170:173], v160
	ds_read_b128 v[174:177], v160 offset:1024
	ds_read_b128 v[178:181], v160 offset:2048
	ds_read_b128 v[182:185], v160 offset:3072
	s_add_u32 s26, s44, 0x80000
	s_addc_u32 s27, s45, 0
	s_mov_b32 m0, s62
	v_lshl_add_u64 v[228:229], s[26:27], 0, v[150:151]
	ds_read_b128 v[186:189], v168 offset:32768
	ds_read_b128 v[190:193], v168 offset:33792
	ds_read_b128 v[194:197], v168 offset:34816
	ds_read_b128 v[204:207], v168 offset:35840
	ds_read_b128 v[208:211], v168 offset:36864
	ds_read_b128 v[212:215], v168 offset:37888
	ds_read_b128 v[216:219], v168 offset:38912
	ds_read_b128 v[220:223], v168 offset:39936
	global_load_lds_dwordx4 v[228:229], off
	v_lshl_add_u64 v[228:229], s[26:27], 0, v[148:149]
	s_mov_b32 m0, s63
	s_nop 0
	global_load_lds_dwordx4 v[228:229], off
	s_waitcnt vmcnt(8)
	s_waitcnt lgkmcnt(0)
	s_barrier
	s_setprio 1
	s_waitcnt lgkmcnt(0)
	v_mfma_f32_16x16x32_bf16 v[128:131], v[132:135], v[186:189], v[128:131]
	v_mfma_f32_16x16x32_bf16 v[128:131], v[136:139], v[190:193], v[128:131]
	v_mfma_f32_16x16x32_bf16 v[124:127], v[140:143], v[186:189], v[124:127]
	v_mfma_f32_16x16x32_bf16 v[124:127], v[144:147], v[190:193], v[124:127]
	v_mfma_f32_16x16x32_bf16 v[116:119], v[132:135], v[194:197], v[116:119]
	v_mfma_f32_16x16x32_bf16 v[116:119], v[136:139], v[204:207], v[116:119]
	v_mfma_f32_16x16x32_bf16 v[112:115], v[140:143], v[194:197], v[112:115]
	v_mfma_f32_16x16x32_bf16 v[112:115], v[144:147], v[204:207], v[112:115]
	v_mfma_f32_16x16x32_bf16 v[104:107], v[132:135], v[208:211], v[104:107]
	v_mfma_f32_16x16x32_bf16 v[104:107], v[136:139], v[212:215], v[104:107]
	v_mfma_f32_16x16x32_bf16 v[96:99], v[140:143], v[208:211], v[96:99]
	v_mfma_f32_16x16x32_bf16 v[96:99], v[144:147], v[212:215], v[96:99]
	v_mfma_f32_16x16x32_bf16 v[88:91], v[132:135], v[216:219], v[88:91]
	v_mfma_f32_16x16x32_bf16 v[88:91], v[136:139], v[220:223], v[88:91]
	v_mfma_f32_16x16x32_bf16 v[80:83], v[140:143], v[216:219], v[80:83]
	v_mfma_f32_16x16x32_bf16 v[80:83], v[144:147], v[220:223], v[80:83]
	s_setprio 0
	s_setprio 1
	v_mfma_f32_16x16x32_bf16 v[120:123], v[170:173], v[186:189], v[120:123]
	v_mfma_f32_16x16x32_bf16 v[120:123], v[174:177], v[190:193], v[120:123]
	v_mfma_f32_16x16x32_bf16 v[108:111], v[178:181], v[186:189], v[108:111]
	v_mfma_f32_16x16x32_bf16 v[108:111], v[182:185], v[190:193], v[108:111]
	v_mfma_f32_16x16x32_bf16 v[100:103], v[170:173], v[194:197], v[100:103]
	v_mfma_f32_16x16x32_bf16 v[100:103], v[174:177], v[204:207], v[100:103]
	v_mfma_f32_16x16x32_bf16 v[92:95], v[178:181], v[194:197], v[92:95]
	v_mfma_f32_16x16x32_bf16 v[92:95], v[182:185], v[204:207], v[92:95]
	v_mfma_f32_16x16x32_bf16 v[84:87], v[170:173], v[208:211], v[84:87]
	v_mfma_f32_16x16x32_bf16 v[84:87], v[174:177], v[212:215], v[84:87]
	v_mfma_f32_16x16x32_bf16 v[76:79], v[178:181], v[208:211], v[76:79]
	v_mfma_f32_16x16x32_bf16 v[76:79], v[182:185], v[212:215], v[76:79]
	v_mfma_f32_16x16x32_bf16 v[72:75], v[170:173], v[216:219], v[72:75]
	v_mfma_f32_16x16x32_bf16 v[72:75], v[174:177], v[220:223], v[72:75]
	s_setprio 2
	s_barrier
; #define PG8_STAGE(bufoff, gbase, voff) do { _Pragma("unroll") for (int _i = 0; _i < 2; ++_i) \
;         __builtin_amdgcn_global_load_lds((const unsigned*)((const char*)(gbase) + (voff)[_i]), (LAS unsigned*)(lds + (bufoff) + ldsw + _i * 8192), 16, 0, 0); } while (0)
; #define PG8_LDA(dst, b, h) do { _Pragma("unroll") for (int m = 0; m < 4; ++m) _Pragma("unroll") for (int k = 0; k < 2; ++k) dst[m][k] = *(const LAS bf16x8*)(lds + PG8_SA(b, h) + aoff + m * 2048 + k * 1024); } while (0)
; #define PG8_LDB(dst, b, h) do { _Pragma("unroll") for (int n = 0; n < 2; ++n) _Pragma("unroll") for (int k = 0; k < 2; ++k) dst[n][k] = *(const LAS bf16x8*)(lds + PG8_SB(b, h) + boff + n * 2048 + k * 1024); } while (0)
; #define PG8_WAIT_V(n) asm volatile("s_waitcnt vmcnt(" #n ")" ::: "memory")
; #define PG8_BAR __builtin_amdgcn_s_barrier()
; template <class Epi, class Sched, bool ALIGN_EPI = true>
; __device__ __forceinline__ void gemm_phase(LAS unsigned char* lds, const Gemm g, const Sched& S, const Epi& E) {
;     ...
;         for (int t = 0; t < nt; t += 2) {
;             const bool last = (t == nt - 2);
;             const char* a1 = cA + (size_t)(t + 1) * kstep;
;             const char* a2 = last ? nA : cA + (size_t)(t + 2) * kstep; const char* b2 = last ? nB : cB + (size_t)(t + 2) * kstep;
;             const char* a3 = a2 + kstep; const char* b3 = b2 + kstep;
;             PG8_LDB(B0, 0, 0); PG8_LDB(B1, 0, 1); PG8_SCHED; PG8_LDA(At, 0, 0); PG8_STAGE(PG8_SA(1, 1), a1 + hA, voffA);
;             PG8_WAIT_V(8); PG8_WAIT_L(0); PG8_BAR; PG8_MMA(0, 0, At, B0); PG8_MMA(0, 1, At, B1); PG8_BAR; PG8_SCHED;
;             PG8_LDA(At, 0, 1); PG8_STAGE(PG8_SB(0, 0), b2, voffB); PG8_STAGE(PG8_SB(0, 1), b2 + hB, voffB); PG8_STAGE(PG8_SA(0, 0), a2, voffA);
;             PG8_WAIT_V(8); PG8_WAIT_L(0); PG8_BAR; PG8_MMA(1, 0, At, B0); PG8_MMA(1, 1, At, B1); PG8_BAR; PG8_SCHED;
;             PG8_LDB(B0, 1, 0); PG8_LDB(B1, 1, 1); PG8_SCHED; PG8_LDA(At, 1, 0); PG8_STAGE(PG8_SA(0, 1), a2 + hA, voffA);
;             PG8_WAIT_V(8); PG8_WAIT_L(0); PG8_BAR; PG8_MMA(0, 0, At, B0); PG8_MMA(0, 1, At, B1); PG8_BAR; PG8_SCHED;
;             PG8_LDA(At, 1, 1); PG8_STAGE(PG8_SB(1, 0), b3, voffB); PG8_STAGE(PG8_SB(1, 1), b3 + hB, voffB); PG8_STAGE(PG8_SA(1, 0), a3, voffA);
;             PG8_WAIT_V(8); PG8_WAIT_L(0); PG8_BAR; PG8_MMA(1, 0, At, B0); PG8_MMA(1, 1, At, B1); PG8_BAR; PG8_SCHED;
	v_mfma_f32_16x16x32_bf16 v[68:71], v[178:181], v[216:219], v[68:71]
	v_mfma_f32_16x16x32_bf16 v[68:71], v[182:185], v[220:223], v[68:71]
	s_setprio 0
	s_add_i32 s26, s30, s59
	v_lshl_add_u64 v[156:157], v[156:157], 0, s[86:87]
	s_mov_b32 m0, s26
	ds_read_b128 v[186:189], v168 offset:49152
	ds_read_b128 v[190:193], v168 offset:50176
	ds_read_b128 v[194:197], v168 offset:51200
	ds_read_b128 v[204:207], v168 offset:52224
	ds_read_b128 v[208:211], v168 offset:53248
	ds_read_b128 v[212:215], v168 offset:54272
	ds_read_b128 v[216:219], v168 offset:55296
	ds_read_b128 v[220:223], v168 offset:56320
	global_load_lds_dwordx4 v[156:157], off
	s_add_i32 m0, s26, 0x2000
	s_add_u32 s26, s42, 0x80080
	v_lshl_add_u64 v[156:157], v[164:165], 0, s[86:87]
	s_addc_u32 s27, s43, 0
	s_add_i32 s30, s31, s59
	global_load_lds_dwordx4 v[156:157], off
	v_lshl_add_u64 v[156:157], s[26:27], 0, v[2:3]
	s_mov_b32 m0, s30
	s_nop 0
	global_load_lds_dwordx4 v[156:157], off
	v_lshl_add_u64 v[156:157], s[26:27], 0, v[0:1]
	s_add_i32 m0, s30, 0x2000
	s_nop 0
	global_load_lds_dwordx4 v[156:157], off
	v_lshl_add_u64 v[156:157], v[224:225], 0, s[86:87]
	s_mov_b32 m0, s64
	s_nop 0
	global_load_lds_dwordx4 v[156:157], off
	v_lshl_add_u64 v[156:157], v[226:227], 0, s[86:87]
	s_mov_b32 m0, s65
	s_nop 0
	global_load_lds_dwordx4 v[156:157], off
	s_waitcnt vmcnt(8)
	s_waitcnt lgkmcnt(0)
	s_barrier
	s_setprio 1
	s_waitcnt lgkmcnt(0)
	v_mfma_f32_16x16x32_bf16 v[64:67], v[132:135], v[186:189], v[64:67]
	v_mfma_f32_16x16x32_bf16 v[64:67], v[136:139], v[190:193], v[64:67]
	s_add_i32 s25, s25, 2
	s_add_u32 s6, s6, 0x100
	v_mfma_f32_16x16x32_bf16 v[60:63], v[140:143], v[186:189], v[60:63]
	v_mfma_f32_16x16x32_bf16 v[60:63], v[144:147], v[190:193], v[60:63]
	s_addc_u32 s7, s7, 0
	s_add_u32 s19, s19, 0x100
	v_mfma_f32_16x16x32_bf16 v[56:59], v[132:135], v[194:197], v[56:59]
	v_mfma_f32_16x16x32_bf16 v[56:59], v[136:139], v[204:207], v[56:59]
	s_addc_u32 s24, s24, 0
	s_add_u32 s26, s6, 0xfff80080
	v_mfma_f32_16x16x32_bf16 v[48:51], v[140:143], v[194:197], v[48:51]
	v_mfma_f32_16x16x32_bf16 v[48:51], v[144:147], v[204:207], v[48:51]
	s_addc_u32 s27, s7, -1
	s_add_i32 s30, 0, 0x10000
	v_mfma_f32_16x16x32_bf16 v[40:43], v[132:135], v[208:211], v[40:43]
	v_mfma_f32_16x16x32_bf16 v[40:43], v[136:139], v[212:215], v[40:43]
	s_cmp_eq_u32 s25, 28
	s_cselect_b32 s45, s15, s27
	v_mfma_f32_16x16x32_bf16 v[32:35], v[140:143], v[208:211], v[32:35]
	v_mfma_f32_16x16x32_bf16 v[32:35], v[144:147], v[212:215], v[32:35]
	s_cselect_b32 s44, s17, s26
	s_cselect_b32 s43, s13, s24
	v_mfma_f32_16x16x32_bf16 v[24:27], v[132:135], v[216:219], v[24:27]
	v_mfma_f32_16x16x32_bf16 v[24:27], v[136:139], v[220:223], v[24:27]
	s_cselect_b32 s42, s18, s19
	s_add_i32 s31, 0, 0x14000
	v_mfma_f32_16x16x32_bf16 v[16:19], v[140:143], v[216:219], v[16:19]
	v_mfma_f32_16x16x32_bf16 v[16:19], v[144:147], v[220:223], v[16:19]
	s_setprio 0
	s_setprio 1
	v_mfma_f32_16x16x32_bf16 v[52:55], v[170:173], v[186:189], v[52:55]
	v_mfma_f32_16x16x32_bf16 v[52:55], v[174:177], v[190:193], v[52:55]
	v_mfma_f32_16x16x32_bf16 v[44:47], v[178:181], v[186:189], v[44:47]
	v_mfma_f32_16x16x32_bf16 v[44:47], v[182:185], v[190:193], v[44:47]
	v_mfma_f32_16x16x32_bf16 v[36:39], v[170:173], v[194:197], v[36:39]
	v_mfma_f32_16x16x32_bf16 v[36:39], v[174:177], v[204:207], v[36:39]
	v_mfma_f32_16x16x32_bf16 v[28:31], v[178:181], v[194:197], v[28:31]
	v_mfma_f32_16x16x32_bf16 v[28:31], v[182:185], v[204:207], v[28:31]
	v_mfma_f32_16x16x32_bf16 v[20:23], v[170:173], v[208:211], v[20:23]
	v_mfma_f32_16x16x32_bf16 v[20:23], v[174:177], v[212:215], v[20:23]
	v_mfma_f32_16x16x32_bf16 v[12:15], v[178:181], v[208:211], v[12:15]
	v_mfma_f32_16x16x32_bf16 v[12:15], v[182:185], v[212:215], v[12:15]
	v_mfma_f32_16x16x32_bf16 v[8:11], v[170:173], v[216:219], v[8:11]
	v_mfma_f32_16x16x32_bf16 v[8:11], v[174:177], v[220:223], v[8:11]
	s_setprio 2
	s_barrier
	v_mfma_f32_16x16x32_bf16 v[4:7], v[178:181], v[216:219], v[4:7]
	v_mfma_f32_16x16x32_bf16 v[4:7], v[182:185], v[220:223], v[4:7]
	s_setprio 0
	s_cmp_gt_u32 s25, 29
	s_cbranch_scc1 .Lpeel_exit_77
.LBB0_77:
	v_add_u32_e32 v144, s30, v166
	v_add_u32_e32 v156, s31, v166
	ds_read_b128 v[132:135], v144
	ds_read_b128 v[136:139], v144 offset:1024
	ds_read_b128 v[140:143], v144 offset:2048
	ds_read_b128 v[144:147], v144 offset:3072
	ds_read_b128 v[170:173], v156
	ds_read_b128 v[174:177], v156 offset:1024
	ds_read_b128 v[178:181], v156 offset:2048
	ds_read_b128 v[182:185], v156 offset:3072
	v_lshl_add_u64 v[156:157], s[6:7], 0, v[152:153]
	s_add_i32 m0, s60, 0xc000
	ds_read_b128 v[186:189], v168
	ds_read_b128 v[190:193], v168 offset:1024
	ds_read_b128 v[194:197], v168 offset:2048
	ds_read_b128 v[204:207], v168 offset:3072
	ds_read_b128 v[208:211], v168 offset:4096
	ds_read_b128 v[212:215], v168 offset:5120
	ds_read_b128 v[216:219], v168 offset:6144
	ds_read_b128 v[220:223], v168 offset:7168
	global_load_lds_dwordx4 v[156:157], off
	v_lshl_add_u64 v[156:157], s[6:7], 0, v[154:155]
	s_add_i32 m0, s60, 0xe000
	s_nop 0
	global_load_lds_dwordx4 v[156:157], off
	s_waitcnt vmcnt(8)
	s_waitcnt lgkmcnt(0)
	s_barrier
; #define PG8_STAGE(bufoff, gbase, voff) do { _Pragma("unroll") for (int _i = 0; _i < 2; ++_i) \
;         __builtin_amdgcn_global_load_lds((const unsigned*)((const char*)(gbase) + (voff)[_i]), (LAS unsigned*)(lds + (bufoff) + ldsw + _i * 8192), 16, 0, 0); } while (0)
; #define PG8_LDA(dst, b, h) do { _Pragma("unroll") for (int m = 0; m < 4; ++m) _Pragma("unroll") for (int k = 0; k < 2; ++k) dst[m][k] = *(const LAS bf16x8*)(lds + PG8_SA(b, h) + aoff + m * 2048 + k * 1024); } while (0)
; #define PG8_MMA(ai, bj, At, Bt) do { __builtin_amdgcn_s_setprio(1); _Pragma("unroll") for (int m = 0; m < 4; ++m) _Pragma("unroll") for (int n = 0; n < 2; ++n) _Pragma("unroll") for (int k = 0; k < 2; ++k) \
;         acc[ai][bj][m][n] = __builtin_amdgcn_mfma_f32_16x16x32_bf16(Bt[n][k], At[m][k], acc[ai][bj][m][n], 0, 0, 0); __builtin_amdgcn_s_setprio(0); } while (0)
; #define PG8_WAIT_V(n) asm volatile("s_waitcnt vmcnt(" #n ")" ::: "memory")
; #define PG8_WAIT_L(n) asm volatile("s_waitcnt lgkmcnt(" #n ")" ::: "memory")
; #define PG8_BAR __builtin_amdgcn_s_barrier()
; #define PG8_SCHED __builtin_amdgcn_sched_barrier(0)
; template <class Epi, class Sched, bool ALIGN_EPI = true>
; __device__ __forceinline__ void gemm_phase(LAS unsigned char* lds, const Gemm g, const Sched& S, const Epi& E) {
;     ...
;             PG8_WAIT_V(8); PG8_WAIT_L(0); PG8_BAR; PG8_MMA(0, 0, At, B0); PG8_MMA(0, 1, At, B1); PG8_BAR; PG8_SCHED;
;             PG8_LDA(At, 0, 1); PG8_STAGE(PG8_SB(0, 0), b2, voffB); PG8_STAGE(PG8_SB(0, 1), b2 + hB, voffB); PG8_STAGE(PG8_SA(0, 0), a2, voffA);
;             PG8_WAIT_V(8); PG8_WAIT_L(0); PG8_BAR; PG8_MMA(1, 0, At, B0); PG8_MMA(1, 1, At, B1); PG8_BAR; PG8_SCHED;
	s_setprio 1
	s_waitcnt lgkmcnt(0)
	v_mfma_f32_16x16x32_bf16 v[128:131], v[132:135], v[186:189], v[128:131]
	v_mfma_f32_16x16x32_bf16 v[128:131], v[136:139], v[190:193], v[128:131]
	v_mfma_f32_16x16x32_bf16 v[124:127], v[140:143], v[186:189], v[124:127]
	v_mfma_f32_16x16x32_bf16 v[124:127], v[144:147], v[190:193], v[124:127]
	v_mfma_f32_16x16x32_bf16 v[116:119], v[132:135], v[194:197], v[116:119]
	v_mfma_f32_16x16x32_bf16 v[116:119], v[136:139], v[204:207], v[116:119]
	v_mfma_f32_16x16x32_bf16 v[112:115], v[140:143], v[194:197], v[112:115]
	v_mfma_f32_16x16x32_bf16 v[112:115], v[144:147], v[204:207], v[112:115]
	v_mfma_f32_16x16x32_bf16 v[104:107], v[132:135], v[208:211], v[104:107]
	v_mfma_f32_16x16x32_bf16 v[104:107], v[136:139], v[212:215], v[104:107]
	v_mfma_f32_16x16x32_bf16 v[96:99], v[140:143], v[208:211], v[96:99]
	v_mfma_f32_16x16x32_bf16 v[96:99], v[144:147], v[212:215], v[96:99]
	v_mfma_f32_16x16x32_bf16 v[88:91], v[132:135], v[216:219], v[88:91]
	v_mfma_f32_16x16x32_bf16 v[88:91], v[136:139], v[220:223], v[88:91]
	v_mfma_f32_16x16x32_bf16 v[80:83], v[140:143], v[216:219], v[80:83]
	v_mfma_f32_16x16x32_bf16 v[80:83], v[144:147], v[220:223], v[80:83]
	s_setprio 0
	s_setprio 1
	v_mfma_f32_16x16x32_bf16 v[120:123], v[170:173], v[186:189], v[120:123]
	v_mfma_f32_16x16x32_bf16 v[120:123], v[174:177], v[190:193], v[120:123]
	v_mfma_f32_16x16x32_bf16 v[108:111], v[178:181], v[186:189], v[108:111]
	v_mfma_f32_16x16x32_bf16 v[108:111], v[182:185], v[190:193], v[108:111]
	v_mfma_f32_16x16x32_bf16 v[100:103], v[170:173], v[194:197], v[100:103]
	v_mfma_f32_16x16x32_bf16 v[100:103], v[174:177], v[204:207], v[100:103]
	v_mfma_f32_16x16x32_bf16 v[92:95], v[178:181], v[194:197], v[92:95]
	v_mfma_f32_16x16x32_bf16 v[92:95], v[182:185], v[204:207], v[92:95]
	v_mfma_f32_16x16x32_bf16 v[84:87], v[170:173], v[208:211], v[84:87]
	v_mfma_f32_16x16x32_bf16 v[84:87], v[174:177], v[212:215], v[84:87]
	v_mfma_f32_16x16x32_bf16 v[76:79], v[178:181], v[208:211], v[76:79]
	v_mfma_f32_16x16x32_bf16 v[76:79], v[182:185], v[212:215], v[76:79]
	v_mfma_f32_16x16x32_bf16 v[72:75], v[170:173], v[216:219], v[72:75]
	v_mfma_f32_16x16x32_bf16 v[72:75], v[174:177], v[220:223], v[72:75]
	s_setprio 2
	s_barrier
	v_mfma_f32_16x16x32_bf16 v[68:71], v[178:181], v[216:219], v[68:71]
	v_mfma_f32_16x16x32_bf16 v[68:71], v[182:185], v[220:223], v[68:71]
	s_setprio 0
	s_add_i32 s26, s30, s59
	v_lshl_add_u64 v[156:157], s[42:43], 0, v[2:3]
	s_mov_b32 m0, s26
	ds_read_b128 v[186:189], v168 offset:16384
	ds_read_b128 v[190:193], v168 offset:17408
	ds_read_b128 v[194:197], v168 offset:18432
	ds_read_b128 v[204:207], v168 offset:19456
	ds_read_b128 v[208:211], v168 offset:20480
	ds_read_b128 v[212:215], v168 offset:21504
	ds_read_b128 v[216:219], v168 offset:22528
	ds_read_b128 v[220:223], v168 offset:23552
	global_load_lds_dwordx4 v[156:157], off
	s_add_i32 m0, s26, 0x2000
	s_add_u32 s26, s42, 0x80000
	v_lshl_add_u64 v[164:165], s[42:43], 0, v[0:1]
	s_addc_u32 s27, s43, 0
	s_add_i32 s30, s31, s59
	global_load_lds_dwordx4 v[164:165], off
	v_lshl_add_u64 v[224:225], s[26:27], 0, v[2:3]
	s_mov_b32 m0, s30
	v_lshl_add_u64 v[226:227], s[44:45], 0, v[148:149]
	global_load_lds_dwordx4 v[224:225], off
	v_lshl_add_u64 v[224:225], s[26:27], 0, v[0:1]
	s_add_i32 m0, s30, 0x2000
	s_nop 0
	global_load_lds_dwordx4 v[224:225], off
	v_lshl_add_u64 v[224:225], s[44:45], 0, v[150:151]
	s_mov_b32 m0, s60
	s_nop 0
	global_load_lds_dwordx4 v[224:225], off
	s_mov_b32 m0, s61
	s_nop 0
	global_load_lds_dwordx4 v[226:227], off
	s_waitcnt vmcnt(8)
	s_waitcnt lgkmcnt(0)
	s_barrier
	s_setprio 1
	s_waitcnt lgkmcnt(0)
	v_mfma_f32_16x16x32_bf16 v[64:67], v[132:135], v[186:189], v[64:67]
	v_mfma_f32_16x16x32_bf16 v[64:67], v[136:139], v[190:193], v[64:67]
	v_mfma_f32_16x16x32_bf16 v[60:63], v[140:143], v[186:189], v[60:63]
	v_mfma_f32_16x16x32_bf16 v[60:63], v[144:147], v[190:193], v[60:63]
	v_mfma_f32_16x16x32_bf16 v[56:59], v[132:135], v[194:197], v[56:59]
	v_mfma_f32_16x16x32_bf16 v[56:59], v[136:139], v[204:207], v[56:59]
	v_mfma_f32_16x16x32_bf16 v[48:51], v[140:143], v[194:197], v[48:51]
	v_mfma_f32_16x16x32_bf16 v[48:51], v[144:147], v[204:207], v[48:51]
	v_mfma_f32_16x16x32_bf16 v[40:43], v[132:135], v[208:211], v[40:43]
	v_mfma_f32_16x16x32_bf16 v[40:43], v[136:139], v[212:215], v[40:43]
	v_mfma_f32_16x16x32_bf16 v[32:35], v[140:143], v[208:211], v[32:35]
	v_mfma_f32_16x16x32_bf16 v[32:35], v[144:147], v[212:215], v[32:35]
	v_mfma_f32_16x16x32_bf16 v[24:27], v[132:135], v[216:219], v[24:27]
	v_mfma_f32_16x16x32_bf16 v[24:27], v[136:139], v[220:223], v[24:27]
	v_mfma_f32_16x16x32_bf16 v[16:19], v[140:143], v[216:219], v[16:19]
	v_mfma_f32_16x16x32_bf16 v[16:19], v[144:147], v[220:223], v[16:19]
	s_setprio 0
	s_setprio 1
	v_mfma_f32_16x16x32_bf16 v[52:55], v[170:173], v[186:189], v[52:55]
	v_mfma_f32_16x16x32_bf16 v[52:55], v[174:177], v[190:193], v[52:55]
	v_mfma_f32_16x16x32_bf16 v[44:47], v[178:181], v[186:189], v[44:47]
	v_mfma_f32_16x16x32_bf16 v[44:47], v[182:185], v[190:193], v[44:47]
	v_mfma_f32_16x16x32_bf16 v[36:39], v[170:173], v[194:197], v[36:39]
	v_mfma_f32_16x16x32_bf16 v[36:39], v[174:177], v[204:207], v[36:39]
	v_mfma_f32_16x16x32_bf16 v[28:31], v[178:181], v[194:197], v[28:31]
	v_mfma_f32_16x16x32_bf16 v[28:31], v[182:185], v[204:207], v[28:31]
	v_mfma_f32_16x16x32_bf16 v[20:23], v[170:173], v[208:211], v[20:23]
	v_mfma_f32_16x16x32_bf16 v[20:23], v[174:177], v[212:215], v[20:23]
	v_mfma_f32_16x16x32_bf16 v[12:15], v[178:181], v[208:211], v[12:15]
	v_mfma_f32_16x16x32_bf16 v[12:15], v[182:185], v[212:215], v[12:15]
	v_mfma_f32_16x16x32_bf16 v[8:11], v[170:173], v[216:219], v[8:11]
	v_mfma_f32_16x16x32_bf16 v[8:11], v[174:177], v[220:223], v[8:11]
	s_setprio 2
	s_barrier
; #define PG8_STAGE(bufoff, gbase, voff) do { _Pragma("unroll") for (int _i = 0; _i < 2; ++_i) \
;         __builtin_amdgcn_global_load_lds((const unsigned*)((const char*)(gbase) + (voff)[_i]), (LAS unsigned*)(lds + (bufoff) + ldsw + _i * 8192), 16, 0, 0); } while (0)
; #define PG8_LDA(dst, b, h) do { _Pragma("unroll") for (int m = 0; m < 4; ++m) _Pragma("unroll") for (int k = 0; k < 2; ++k) dst[m][k] = *(const LAS bf16x8*)(lds + PG8_SA(b, h) + aoff + m * 2048 + k * 1024); } while (0)
; #define PG8_LDB(dst, b, h) do { _Pragma("unroll") for (int n = 0; n < 2; ++n) _Pragma("unroll") for (int k = 0; k < 2; ++k) dst[n][k] = *(const LAS bf16x8*)(lds + PG8_SB(b, h) + boff + n * 2048 + k * 1024); } while (0)
; #define PG8_MMA(ai, bj, At, Bt) do { __builtin_amdgcn_s_setprio(1); _Pragma("unroll") for (int m = 0; m < 4; ++m) _Pragma("unroll") for (int n = 0; n < 2; ++n) _Pragma("unroll") for (int k = 0; k < 2; ++k) \
;         acc[ai][bj][m][n] = __builtin_amdgcn_mfma_f32_16x16x32_bf16(Bt[n][k], At[m][k], acc[ai][bj][m][n], 0, 0, 0); __builtin_amdgcn_s_setprio(0); } while (0)
; #define PG8_WAIT_V(n) asm volatile("s_waitcnt vmcnt(" #n ")" ::: "memory")
; #define PG8_WAIT_L(n) asm volatile("s_waitcnt lgkmcnt(" #n ")" ::: "memory")
; #define PG8_BAR __builtin_amdgcn_s_barrier()
; #define PG8_SCHED __builtin_amdgcn_sched_barrier(0)
; template <class Epi, class Sched, bool ALIGN_EPI = true>
; __device__ __forceinline__ void gemm_phase(LAS unsigned char* lds, const Gemm g, const Sched& S, const Epi& E) {
;     ...
;             PG8_WAIT_V(8); PG8_WAIT_L(0); PG8_BAR; PG8_MMA(1, 0, At, B0); PG8_MMA(1, 1, At, B1); PG8_BAR; PG8_SCHED;
;             PG8_LDB(B0, 1, 0); PG8_LDB(B1, 1, 1); PG8_SCHED; PG8_LDA(At, 1, 0); PG8_STAGE(PG8_SA(0, 1), a2 + hA, voffA);
;             PG8_WAIT_V(8); PG8_WAIT_L(0); PG8_BAR; PG8_MMA(0, 0, At, B0); PG8_MMA(0, 1, At, B1); PG8_BAR; PG8_SCHED;
	v_mfma_f32_16x16x32_bf16 v[4:7], v[178:181], v[216:219], v[4:7]
	v_mfma_f32_16x16x32_bf16 v[4:7], v[182:185], v[220:223], v[4:7]
	s_setprio 0
	s_add_i32 s30, 0, 0x18000
	s_add_i32 s31, 0, 0x1c000
	v_add_u32_e32 v144, s30, v166
	v_add_u32_e32 v160, s31, v166
	ds_read_b128 v[132:135], v144
	ds_read_b128 v[136:139], v144 offset:1024
	ds_read_b128 v[140:143], v144 offset:2048
	ds_read_b128 v[144:147], v144 offset:3072
	ds_read_b128 v[170:173], v160
	ds_read_b128 v[174:177], v160 offset:1024
	ds_read_b128 v[178:181], v160 offset:2048
	ds_read_b128 v[182:185], v160 offset:3072
	s_add_u32 s26, s44, 0x80000
	s_addc_u32 s27, s45, 0
	s_mov_b32 m0, s62
	v_lshl_add_u64 v[228:229], s[26:27], 0, v[150:151]
	ds_read_b128 v[186:189], v168 offset:32768
	ds_read_b128 v[190:193], v168 offset:33792
	ds_read_b128 v[194:197], v168 offset:34816
	ds_read_b128 v[204:207], v168 offset:35840
	ds_read_b128 v[208:211], v168 offset:36864
	ds_read_b128 v[212:215], v168 offset:37888
	ds_read_b128 v[216:219], v168 offset:38912
	ds_read_b128 v[220:223], v168 offset:39936
	global_load_lds_dwordx4 v[228:229], off
	v_lshl_add_u64 v[228:229], s[26:27], 0, v[148:149]
	s_mov_b32 m0, s63
	s_nop 0
	global_load_lds_dwordx4 v[228:229], off
	s_waitcnt vmcnt(8)
	s_waitcnt lgkmcnt(0)
	s_barrier
	s_setprio 1
	s_waitcnt lgkmcnt(0)
	v_mfma_f32_16x16x32_bf16 v[128:131], v[132:135], v[186:189], v[128:131]
	v_mfma_f32_16x16x32_bf16 v[128:131], v[136:139], v[190:193], v[128:131]
	v_mfma_f32_16x16x32_bf16 v[124:127], v[140:143], v[186:189], v[124:127]
	v_mfma_f32_16x16x32_bf16 v[124:127], v[144:147], v[190:193], v[124:127]
	v_mfma_f32_16x16x32_bf16 v[116:119], v[132:135], v[194:197], v[116:119]
	v_mfma_f32_16x16x32_bf16 v[116:119], v[136:139], v[204:207], v[116:119]
	v_mfma_f32_16x16x32_bf16 v[112:115], v[140:143], v[194:197], v[112:115]
	v_mfma_f32_16x16x32_bf16 v[112:115], v[144:147], v[204:207], v[112:115]
	v_mfma_f32_16x16x32_bf16 v[104:107], v[132:135], v[208:211], v[104:107]
	v_mfma_f32_16x16x32_bf16 v[104:107], v[136:139], v[212:215], v[104:107]
	v_mfma_f32_16x16x32_bf16 v[96:99], v[140:143], v[208:211], v[96:99]
	v_mfma_f32_16x16x32_bf16 v[96:99], v[144:147], v[212:215], v[96:99]
	v_mfma_f32_16x16x32_bf16 v[88:91], v[132:135], v[216:219], v[88:91]
	v_mfma_f32_16x16x32_bf16 v[88:91], v[136:139], v[220:223], v[88:91]
	v_mfma_f32_16x16x32_bf16 v[80:83], v[140:143], v[216:219], v[80:83]
	v_mfma_f32_16x16x32_bf16 v[80:83], v[144:147], v[220:223], v[80:83]
	s_setprio 0
	s_setprio 1
	v_mfma_f32_16x16x32_bf16 v[120:123], v[170:173], v[186:189], v[120:123]
	v_mfma_f32_16x16x32_bf16 v[120:123], v[174:177], v[190:193], v[120:123]
	v_mfma_f32_16x16x32_bf16 v[108:111], v[178:181], v[186:189], v[108:111]
	v_mfma_f32_16x16x32_bf16 v[108:111], v[182:185], v[190:193], v[108:111]
	v_mfma_f32_16x16x32_bf16 v[100:103], v[170:173], v[194:197], v[100:103]
	v_mfma_f32_16x16x32_bf16 v[100:103], v[174:177], v[204:207], v[100:103]
	v_mfma_f32_16x16x32_bf16 v[92:95], v[178:181], v[194:197], v[92:95]
	v_mfma_f32_16x16x32_bf16 v[92:95], v[182:185], v[204:207], v[92:95]
	v_mfma_f32_16x16x32_bf16 v[84:87], v[170:173], v[208:211], v[84:87]
	v_mfma_f32_16x16x32_bf16 v[84:87], v[174:177], v[212:215], v[84:87]
	v_mfma_f32_16x16x32_bf16 v[76:79], v[178:181], v[208:211], v[76:79]
	v_mfma_f32_16x16x32_bf16 v[76:79], v[182:185], v[212:215], v[76:79]
	v_mfma_f32_16x16x32_bf16 v[72:75], v[170:173], v[216:219], v[72:75]
	v_mfma_f32_16x16x32_bf16 v[72:75], v[174:177], v[220:223], v[72:75]
	s_setprio 2
	s_barrier
; #define PG8_STAGE(bufoff, gbase, voff) do { _Pragma("unroll") for (int _i = 0; _i < 2; ++_i) \
;         __builtin_amdgcn_global_load_lds((const unsigned*)((const char*)(gbase) + (voff)[_i]), (LAS unsigned*)(lds + (bufoff) + ldsw + _i * 8192), 16, 0, 0); } while (0)
; #define PG8_LDA(dst, b, h) do { _Pragma("unroll") for (int m = 0; m < 4; ++m) _Pragma("unroll") for (int k = 0; k < 2; ++k) dst[m][k] = *(const LAS bf16x8*)(lds + PG8_SA(b, h) + aoff + m * 2048 + k * 1024); } while (0)
; #define PG8_LDB(dst, b, h) do { _Pragma("unroll") for (int n = 0; n < 2; ++n) _Pragma("unroll") for (int k = 0; k < 2; ++k) dst[n][k] = *(const LAS bf16x8*)(lds + PG8_SB(b, h) + boff + n * 2048 + k * 1024); } while (0)
; #define PG8_WAIT_V(n) asm volatile("s_waitcnt vmcnt(" #n ")" ::: "memory")
; #define PG8_BAR __builtin_amdgcn_s_barrier()
; template <class Epi, class Sched, bool ALIGN_EPI = true>
; __device__ __forceinline__ void gemm_phase(LAS unsigned char* lds, const Gemm g, const Sched& S, const Epi& E) {
;     ...
;         for (int t = 0; t < nt; t += 2) {
;             const bool last = (t == nt - 2);
;             const char* a1 = cA + (size_t)(t + 1) * kstep;
;             const char* a2 = last ? nA : cA + (size_t)(t + 2) * kstep; const char* b2 = last ? nB : cB + (size_t)(t + 2) * kstep;
;             const char* a3 = a2 + kstep; const char* b3 = b2 + kstep;
;             PG8_LDB(B0, 0, 0); PG8_LDB(B1, 0, 1); PG8_SCHED; PG8_LDA(At, 0, 0); PG8_STAGE(PG8_SA(1, 1), a1 + hA, voffA);
;             PG8_WAIT_V(8); PG8_WAIT_L(0); PG8_BAR; PG8_MMA(0, 0, At, B0); PG8_MMA(0, 1, At, B1); PG8_BAR; PG8_SCHED;
;             PG8_LDA(At, 0, 1); PG8_STAGE(PG8_SB(0, 0), b2, voffB); PG8_STAGE(PG8_SB(0, 1), b2 + hB, voffB); PG8_STAGE(PG8_SA(0, 0), a2, voffA);
;             PG8_WAIT_V(8); PG8_WAIT_L(0); PG8_BAR; PG8_MMA(1, 0, At, B0); PG8_MMA(1, 1, At, B1); PG8_BAR; PG8_SCHED;
;             PG8_LDB(B0, 1, 0); PG8_LDB(B1, 1, 1); PG8_SCHED; PG8_LDA(At, 1, 0); PG8_STAGE(PG8_SA(0, 1), a2 + hA, voffA);
;             PG8_WAIT_V(8); PG8_WAIT_L(0); PG8_BAR; PG8_MMA(0, 0, At, B0); PG8_MMA(0, 1, At, B1); PG8_BAR; PG8_SCHED;
;             PG8_LDA(At, 1, 1); PG8_STAGE(PG8_SB(1, 0), b3, voffB); PG8_STAGE(PG8_SB(1, 1), b3 + hB, voffB); PG8_STAGE(PG8_SA(1, 0), a3, voffA);
;             PG8_WAIT_V(8); PG8_WAIT_L(0); PG8_BAR; PG8_MMA(1, 0, At, B0); PG8_MMA(1, 1, At, B1); PG8_BAR; PG8_SCHED;
	v_mfma_f32_16x16x32_bf16 v[68:71], v[178:181], v[216:219], v[68:71]
	v_mfma_f32_16x16x32_bf16 v[68:71], v[182:185], v[220:223], v[68:71]
	s_setprio 0
	s_add_i32 s26, s30, s59
	v_lshl_add_u64 v[156:157], v[156:157], 0, s[86:87]
	s_mov_b32 m0, s26
	ds_read_b128 v[186:189], v168 offset:49152
	ds_read_b128 v[190:193], v168 offset:50176
	ds_read_b128 v[194:197], v168 offset:51200
	ds_read_b128 v[204:207], v168 offset:52224
	ds_read_b128 v[208:211], v168 offset:53248
	ds_read_b128 v[212:215], v168 offset:54272
	ds_read_b128 v[216:219], v168 offset:55296
	ds_read_b128 v[220:223], v168 offset:56320
	global_load_lds_dwordx4 v[156:157], off
	s_add_i32 m0, s26, 0x2000
	s_add_u32 s26, s42, 0x80080
	v_lshl_add_u64 v[156:157], v[164:165], 0, s[86:87]
	s_addc_u32 s27, s43, 0
	s_add_i32 s30, s31, s59
	global_load_lds_dwordx4 v[156:157], off
	v_lshl_add_u64 v[156:157], s[26:27], 0, v[2:3]
	s_mov_b32 m0, s30
	s_nop 0
	global_load_lds_dwordx4 v[156:157], off
	v_lshl_add_u64 v[156:157], s[26:27], 0, v[0:1]
	s_add_i32 m0, s30, 0x2000
	s_nop 0
	global_load_lds_dwordx4 v[156:157], off
	v_lshl_add_u64 v[156:157], v[224:225], 0, s[86:87]
	s_mov_b32 m0, s64
	s_nop 0
	global_load_lds_dwordx4 v[156:157], off
	v_lshl_add_u64 v[156:157], v[226:227], 0, s[86:87]
	s_mov_b32 m0, s65
	s_nop 0
	global_load_lds_dwordx4 v[156:157], off
	s_waitcnt vmcnt(8)
	s_waitcnt lgkmcnt(0)
	s_barrier
	s_setprio 1
	s_waitcnt lgkmcnt(0)
	v_mfma_f32_16x16x32_bf16 v[64:67], v[132:135], v[186:189], v[64:67]
	v_mfma_f32_16x16x32_bf16 v[64:67], v[136:139], v[190:193], v[64:67]
	s_add_i32 s25, s25, 2
	s_add_u32 s6, s6, 0x100
	v_mfma_f32_16x16x32_bf16 v[60:63], v[140:143], v[186:189], v[60:63]
	v_mfma_f32_16x16x32_bf16 v[60:63], v[144:147], v[190:193], v[60:63]
	s_addc_u32 s7, s7, 0
	s_add_u32 s19, s19, 0x100
	v_mfma_f32_16x16x32_bf16 v[56:59], v[132:135], v[194:197], v[56:59]
	v_mfma_f32_16x16x32_bf16 v[56:59], v[136:139], v[204:207], v[56:59]
	s_addc_u32 s24, s24, 0
	s_add_u32 s26, s6, 0xfff80080
	v_mfma_f32_16x16x32_bf16 v[48:51], v[140:143], v[194:197], v[48:51]
	v_mfma_f32_16x16x32_bf16 v[48:51], v[144:147], v[204:207], v[48:51]
	s_addc_u32 s27, s7, -1
	s_add_i32 s30, 0, 0x10000
	v_mfma_f32_16x16x32_bf16 v[40:43], v[132:135], v[208:211], v[40:43]
	v_mfma_f32_16x16x32_bf16 v[40:43], v[136:139], v[212:215], v[40:43]
	s_cmp_eq_u32 s25, 28
	s_cselect_b32 s45, s15, s27
	v_mfma_f32_16x16x32_bf16 v[32:35], v[140:143], v[208:211], v[32:35]
	v_mfma_f32_16x16x32_bf16 v[32:35], v[144:147], v[212:215], v[32:35]
	s_cselect_b32 s44, s17, s26
	s_cselect_b32 s43, s13, s24
	v_mfma_f32_16x16x32_bf16 v[24:27], v[132:135], v[216:219], v[24:27]
	v_mfma_f32_16x16x32_bf16 v[24:27], v[136:139], v[220:223], v[24:27]
	s_cselect_b32 s42, s18, s19
	s_add_i32 s31, 0, 0x14000
	v_mfma_f32_16x16x32_bf16 v[16:19], v[140:143], v[216:219], v[16:19]
	v_mfma_f32_16x16x32_bf16 v[16:19], v[144:147], v[220:223], v[16:19]
	s_setprio 0
	s_setprio 1
	v_mfma_f32_16x16x32_bf16 v[52:55], v[170:173], v[186:189], v[52:55]
	v_mfma_f32_16x16x32_bf16 v[52:55], v[174:177], v[190:193], v[52:55]
	v_mfma_f32_16x16x32_bf16 v[44:47], v[178:181], v[186:189], v[44:47]
	v_mfma_f32_16x16x32_bf16 v[44:47], v[182:185], v[190:193], v[44:47]
	v_mfma_f32_16x16x32_bf16 v[36:39], v[170:173], v[194:197], v[36:39]
	v_mfma_f32_16x16x32_bf16 v[36:39], v[174:177], v[204:207], v[36:39]
	v_mfma_f32_16x16x32_bf16 v[28:31], v[178:181], v[194:197], v[28:31]
	v_mfma_f32_16x16x32_bf16 v[28:31], v[182:185], v[204:207], v[28:31]
	v_mfma_f32_16x16x32_bf16 v[20:23], v[170:173], v[208:211], v[20:23]
	v_mfma_f32_16x16x32_bf16 v[20:23], v[174:177], v[212:215], v[20:23]
	v_mfma_f32_16x16x32_bf16 v[12:15], v[178:181], v[208:211], v[12:15]
	v_mfma_f32_16x16x32_bf16 v[12:15], v[182:185], v[212:215], v[12:15]
	v_mfma_f32_16x16x32_bf16 v[8:11], v[170:173], v[216:219], v[8:11]
	v_mfma_f32_16x16x32_bf16 v[8:11], v[174:177], v[220:223], v[8:11]
	s_setprio 2
	s_barrier
	v_mfma_f32_16x16x32_bf16 v[4:7], v[178:181], v[216:219], v[4:7]
	v_mfma_f32_16x16x32_bf16 v[4:7], v[182:185], v[220:223], v[4:7]
	s_setprio 0
	s_cmp_gt_u32 s25, 29
	s_cbranch_scc0 .LBB0_77

;     __device__ bool next(int i, Unit& u) const { if (i >= 2) return false; const int x = c & 7, j = c >> 3; u.pm = 32 * i + 4 * x + (j & 3); u.pn = j >> 2; return true; }
; #define PG8_STAGE(bufoff, gbase, voff) do { _Pragma("unroll") for (int _i = 0; _i < 2; ++_i) \
;         __builtin_amdgcn_global_load_lds((const unsigned*)((const char*)(gbase) + (voff)[_i]), (LAS unsigned*)(lds + (bufoff) + ldsw + _i * 8192), 16, 0, 0); } while (0)
; #define PG8_LDA(dst, b, h) do { _Pragma("unroll") for (int m = 0; m < 4; ++m) _Pragma("unroll") for (int k = 0; k < 2; ++k) dst[m][k] = *(const LAS bf16x8*)(lds + PG8_SA(b, h) + aoff + m * 2048 + k * 1024); } while (0)
; #define PG8_LDB(dst, b, h) do { _Pragma("unroll") for (int n = 0; n < 2; ++n) _Pragma("unroll") for (int k = 0; k < 2; ++k) dst[n][k] = *(const LAS bf16x8*)(lds + PG8_SB(b, h) + boff + n * 2048 + k * 1024); } while (0)
; #define PG8_WAIT_V(n) asm volatile("s_waitcnt vmcnt(" #n ")" ::: "memory")
; #define PG8_WAIT_L(n) asm volatile("s_waitcnt lgkmcnt(" #n ")" ::: "memory")
; #define PG8_BAR __builtin_amdgcn_s_barrier()
; template <class Epi, class Sched, bool ALIGN_EPI = true>
; __device__ __forceinline__ void gemm_phase(LAS unsigned char* lds, const Gemm g, const Sched& S, const Epi& E) {
;     ...
;         const bool has_next = S.next(ui + 1, nxt);
;         const char* nA = has_next ? (const char*)g.A + ((size_t)nxt.pm * BM * g.lda + (size_t)nxt.pn * g.a_pn_off) * 2 : cA; const char* nB = has_next ? (const char*)g.Bt + (size_t)nxt.pn * BM * g.ldb * 2 : cB;
;         for (int t = 0; t < nt; t += 2) {
;             const bool last = (t == nt - 2);
;             const char* a1 = cA + (size_t)(t + 1) * kstep;
;             const char* a2 = last ? nA : cA + (size_t)(t + 2) * kstep; const char* b2 = last ? nB : cB + (size_t)(t + 2) * kstep;
;             const char* a3 = a2 + kstep; const char* b3 = b2 + kstep;
;             PG8_LDB(B0, 0, 0); PG8_LDB(B1, 0, 1); PG8_SCHED; PG8_LDA(At, 0, 0); PG8_STAGE(PG8_SA(1, 1), a1 + hA, voffA);
;             PG8_WAIT_V(8); PG8_WAIT_L(0); PG8_BAR; PG8_MMA(0, 0, At, B0); PG8_MMA(0, 1, At, B1); PG8_BAR; PG8_SCHED;
;             PG8_LDA(At, 0, 1); PG8_STAGE(PG8_SB(0, 0), b2, voffB); PG8_STAGE(PG8_SB(0, 1), b2 + hB, voffB); PG8_STAGE(PG8_SA(0, 0), a2, voffA);
;             PG8_WAIT_V(8); PG8_WAIT_L(0); PG8_BAR; PG8_MMA(1, 0, At, B0); PG8_MMA(1, 1, At, B1); PG8_BAR; PG8_SCHED;
.LBB0_217:
	s_ashr_i32 s11, s10, 31
	s_lshl_b64 s[12:13], s[10:11], 20
	s_add_u32 s12, s46, s12
	s_addc_u32 s13, s47, s13
	s_and_b64 s[14:15], s[4:5], exec
	s_cselect_b32 s11, s13, s39
	s_cselect_b32 s18, s12, s38
	s_ashr_i32 s9, s8, 31
	s_lshl_b64 s[14:15], s[8:9], 20
	s_add_u32 s14, s44, s14
	s_addc_u32 s15, s45, s15
	s_and_b64 s[24:25], s[4:5], exec
	s_cselect_b32 s9, s15, s41
	s_cselect_b32 s19, s14, s40
	s_add_u32 s38, s38, 0x80080
	s_addc_u32 s39, s39, 0
	s_add_u32 s24, s40, 0x100
	s_addc_u32 s25, s41, 0
	s_mov_b32 s26, -2
	s_add_u32 s27, s38, 0xfff80080
	s_addc_u32 s30, s39, -1
	s_add_i32 s31, 0, 0x10000
	s_cmp_eq_u32 s26, 28
	s_cselect_b32 s43, s11, s30
	s_cselect_b32 s42, s18, s27
	v_add_u32_e32 v156, s31, v145
	s_cselect_b32 s41, s9, s25
	s_cselect_b32 s40, s19, s24
	s_add_i32 s27, 0, 0x14000
	ds_read_b128 v[140:143], v156
	ds_read_b128 v[148:151], v156 offset:1024
	ds_read_b128 v[152:155], v156 offset:2048
	ds_read_b128 v[164:167], v156 offset:3072
	v_add_u32_e32 v156, s27, v145
	ds_read_b128 v[168:171], v156
	ds_read_b128 v[172:175], v156 offset:1024
	ds_read_b128 v[176:179], v156 offset:2048
	ds_read_b128 v[180:183], v156 offset:3072
	v_lshl_add_u64 v[156:157], s[38:39], 0, v[136:137]
	s_add_i32 m0, s58, 0xc000
	ds_read_b128 v[184:187], v147
	ds_read_b128 v[188:191], v147 offset:1024
	ds_read_b128 v[192:195], v147 offset:2048
	ds_read_b128 v[204:207], v147 offset:3072
	ds_read_b128 v[208:211], v147 offset:4096
	ds_read_b128 v[212:215], v147 offset:5120
	ds_read_b128 v[216:219], v147 offset:6144
	ds_read_b128 v[220:223], v147 offset:7168
	global_load_lds_dwordx4 v[156:157], off
	v_lshl_add_u64 v[156:157], s[38:39], 0, v[138:139]
	s_add_i32 m0, s58, 0xe000
	s_nop 0
	global_load_lds_dwordx4 v[156:157], off
	s_waitcnt vmcnt(8)
	s_waitcnt lgkmcnt(0)
	s_barrier
	s_setprio 1
	s_waitcnt lgkmcnt(0)
	v_mfma_f32_16x16x32_bf16 v[128:131], v[140:143], v[184:187], 0
	v_mfma_f32_16x16x32_bf16 v[128:131], v[148:151], v[188:191], v[128:131]
	v_mfma_f32_16x16x32_bf16 v[124:127], v[152:155], v[184:187], 0
	v_mfma_f32_16x16x32_bf16 v[124:127], v[164:167], v[188:191], v[124:127]
	v_mfma_f32_16x16x32_bf16 v[120:123], v[140:143], v[192:195], 0
	v_mfma_f32_16x16x32_bf16 v[120:123], v[148:151], v[204:207], v[120:123]
	v_mfma_f32_16x16x32_bf16 v[112:115], v[152:155], v[192:195], 0
	v_mfma_f32_16x16x32_bf16 v[112:115], v[164:167], v[204:207], v[112:115]
	v_mfma_f32_16x16x32_bf16 v[104:107], v[140:143], v[208:211], 0
	v_mfma_f32_16x16x32_bf16 v[104:107], v[148:151], v[212:215], v[104:107]
	v_mfma_f32_16x16x32_bf16 v[96:99], v[152:155], v[208:211], 0
	v_mfma_f32_16x16x32_bf16 v[96:99], v[164:167], v[212:215], v[96:99]
	v_mfma_f32_16x16x32_bf16 v[88:91], v[140:143], v[216:219], 0
	v_mfma_f32_16x16x32_bf16 v[88:91], v[148:151], v[220:223], v[88:91]
	v_mfma_f32_16x16x32_bf16 v[80:83], v[152:155], v[216:219], 0
	v_mfma_f32_16x16x32_bf16 v[80:83], v[164:167], v[220:223], v[80:83]
	s_setprio 0
	s_setprio 1
	v_mfma_f32_16x16x32_bf16 v[116:119], v[168:171], v[184:187], 0
	v_mfma_f32_16x16x32_bf16 v[116:119], v[172:175], v[188:191], v[116:119]
	v_mfma_f32_16x16x32_bf16 v[108:111], v[176:179], v[184:187], 0
	v_mfma_f32_16x16x32_bf16 v[108:111], v[180:183], v[188:191], v[108:111]
	v_mfma_f32_16x16x32_bf16 v[100:103], v[168:171], v[192:195], 0
	v_mfma_f32_16x16x32_bf16 v[100:103], v[172:175], v[204:207], v[100:103]
	v_mfma_f32_16x16x32_bf16 v[92:95], v[176:179], v[192:195], 0
	v_mfma_f32_16x16x32_bf16 v[92:95], v[180:183], v[204:207], v[92:95]
	v_mfma_f32_16x16x32_bf16 v[84:87], v[168:171], v[208:211], 0
	v_mfma_f32_16x16x32_bf16 v[84:87], v[172:175], v[212:215], v[84:87]
	v_mfma_f32_16x16x32_bf16 v[76:79], v[176:179], v[208:211], 0
	v_mfma_f32_16x16x32_bf16 v[76:79], v[180:183], v[212:215], v[76:79]
	v_mfma_f32_16x16x32_bf16 v[72:75], v[168:171], v[216:219], 0
	v_mfma_f32_16x16x32_bf16 v[72:75], v[172:175], v[220:223], v[72:75]
	s_setprio 2
	s_barrier
	v_mfma_f32_16x16x32_bf16 v[68:71], v[176:179], v[216:219], 0
	v_mfma_f32_16x16x32_bf16 v[68:71], v[180:183], v[220:223], v[68:71]
	s_setprio 0
	s_add_i32 s30, s31, s53
	v_lshl_add_u64 v[156:157], s[40:41], 0, v[2:3]
	s_mov_b32 m0, s30
	ds_read_b128 v[184:187], v147 offset:16384
	ds_read_b128 v[188:191], v147 offset:17408
	ds_read_b128 v[192:195], v147 offset:18432
	ds_read_b128 v[204:207], v147 offset:19456
	ds_read_b128 v[208:211], v147 offset:20480
	ds_read_b128 v[212:215], v147 offset:21504
	ds_read_b128 v[216:219], v147 offset:22528
	ds_read_b128 v[220:223], v147 offset:23552
	global_load_lds_dwordx4 v[156:157], off
	s_add_i32 m0, s30, 0x2000
	s_add_u32 s30, s40, 0x80000
	v_lshl_add_u64 v[196:197], s[40:41], 0, v[0:1]
	s_addc_u32 s31, s41, 0
	s_add_i32 s27, s27, s53
	global_load_lds_dwordx4 v[196:197], off
	v_lshl_add_u64 v[224:225], s[30:31], 0, v[2:3]
	s_mov_b32 m0, s27
	v_lshl_add_u64 v[226:227], s[42:43], 0, v[132:133]
	global_load_lds_dwordx4 v[224:225], off
	v_lshl_add_u64 v[224:225], s[30:31], 0, v[0:1]
	s_add_i32 m0, s27, 0x2000
	s_nop 0
	global_load_lds_dwordx4 v[224:225], off
	v_lshl_add_u64 v[224:225], s[42:43], 0, v[134:135]
	s_mov_b32 m0, s58
	s_nop 0
	global_load_lds_dwordx4 v[224:225], off
	s_mov_b32 m0, s59
	s_nop 0
	global_load_lds_dwordx4 v[226:227], off
	s_waitcnt vmcnt(8)
	s_waitcnt lgkmcnt(0)
	s_barrier
; #define PG8_STAGE(bufoff, gbase, voff) do { _Pragma("unroll") for (int _i = 0; _i < 2; ++_i) \
;         __builtin_amdgcn_global_load_lds((const unsigned*)((const char*)(gbase) + (voff)[_i]), (LAS unsigned*)(lds + (bufoff) + ldsw + _i * 8192), 16, 0, 0); } while (0)
; #define PG8_LDA(dst, b, h) do { _Pragma("unroll") for (int m = 0; m < 4; ++m) _Pragma("unroll") for (int k = 0; k < 2; ++k) dst[m][k] = *(const LAS bf16x8*)(lds + PG8_SA(b, h) + aoff + m * 2048 + k * 1024); } while (0)
; #define PG8_LDB(dst, b, h) do { _Pragma("unroll") for (int n = 0; n < 2; ++n) _Pragma("unroll") for (int k = 0; k < 2; ++k) dst[n][k] = *(const LAS bf16x8*)(lds + PG8_SB(b, h) + boff + n * 2048 + k * 1024); } while (0)
; #define PG8_MMA(ai, bj, At, Bt) do { __builtin_amdgcn_s_setprio(1); _Pragma("unroll") for (int m = 0; m < 4; ++m) _Pragma("unroll") for (int n = 0; n < 2; ++n) _Pragma("unroll") for (int k = 0; k < 2; ++k) \
;         acc[ai][bj][m][n] = __builtin_amdgcn_mfma_f32_16x16x32_bf16(Bt[n][k], At[m][k], acc[ai][bj][m][n], 0, 0, 0); __builtin_amdgcn_s_setprio(0); } while (0)
; #define PG8_WAIT_V(n) asm volatile("s_waitcnt vmcnt(" #n ")" ::: "memory")
; #define PG8_WAIT_L(n) asm volatile("s_waitcnt lgkmcnt(" #n ")" ::: "memory")
; #define PG8_BAR __builtin_amdgcn_s_barrier()
; #define PG8_SCHED __builtin_amdgcn_sched_barrier(0)
; template <class Epi, class Sched, bool ALIGN_EPI = true>
; __device__ __forceinline__ void gemm_phase(LAS unsigned char* lds, const Gemm g, const Sched& S, const Epi& E) {
;     ...
;             PG8_WAIT_V(8); PG8_WAIT_L(0); PG8_BAR; PG8_MMA(1, 0, At, B0); PG8_MMA(1, 1, At, B1); PG8_BAR; PG8_SCHED;
;             PG8_LDB(B0, 1, 0); PG8_LDB(B1, 1, 1); PG8_SCHED; PG8_LDA(At, 1, 0); PG8_STAGE(PG8_SA(0, 1), a2 + hA, voffA);
;             PG8_WAIT_V(8); PG8_WAIT_L(0); PG8_BAR; PG8_MMA(0, 0, At, B0); PG8_MMA(0, 1, At, B1); PG8_BAR; PG8_SCHED;
	s_setprio 1
	s_waitcnt lgkmcnt(0)
	v_mfma_f32_16x16x32_bf16 v[64:67], v[140:143], v[184:187], 0
	v_mfma_f32_16x16x32_bf16 v[64:67], v[148:151], v[188:191], v[64:67]
	v_mfma_f32_16x16x32_bf16 v[60:63], v[152:155], v[184:187], 0
	v_mfma_f32_16x16x32_bf16 v[60:63], v[164:167], v[188:191], v[60:63]
	v_mfma_f32_16x16x32_bf16 v[56:59], v[140:143], v[192:195], 0
	v_mfma_f32_16x16x32_bf16 v[56:59], v[148:151], v[204:207], v[56:59]
	v_mfma_f32_16x16x32_bf16 v[48:51], v[152:155], v[192:195], 0
	v_mfma_f32_16x16x32_bf16 v[48:51], v[164:167], v[204:207], v[48:51]
	v_mfma_f32_16x16x32_bf16 v[40:43], v[140:143], v[208:211], 0
	v_mfma_f32_16x16x32_bf16 v[40:43], v[148:151], v[212:215], v[40:43]
	v_mfma_f32_16x16x32_bf16 v[32:35], v[152:155], v[208:211], 0
	v_mfma_f32_16x16x32_bf16 v[32:35], v[164:167], v[212:215], v[32:35]
	v_mfma_f32_16x16x32_bf16 v[24:27], v[140:143], v[216:219], 0
	v_mfma_f32_16x16x32_bf16 v[24:27], v[148:151], v[220:223], v[24:27]
	v_mfma_f32_16x16x32_bf16 v[16:19], v[152:155], v[216:219], 0
	v_mfma_f32_16x16x32_bf16 v[16:19], v[164:167], v[220:223], v[16:19]
	s_setprio 0
	s_setprio 1
	v_mfma_f32_16x16x32_bf16 v[52:55], v[168:171], v[184:187], 0
	v_mfma_f32_16x16x32_bf16 v[52:55], v[172:175], v[188:191], v[52:55]
	v_mfma_f32_16x16x32_bf16 v[44:47], v[176:179], v[184:187], 0
	v_mfma_f32_16x16x32_bf16 v[44:47], v[180:183], v[188:191], v[44:47]
	v_mfma_f32_16x16x32_bf16 v[36:39], v[168:171], v[192:195], 0
	v_mfma_f32_16x16x32_bf16 v[36:39], v[172:175], v[204:207], v[36:39]
	v_mfma_f32_16x16x32_bf16 v[28:31], v[176:179], v[192:195], 0
	v_mfma_f32_16x16x32_bf16 v[28:31], v[180:183], v[204:207], v[28:31]
	v_mfma_f32_16x16x32_bf16 v[20:23], v[168:171], v[208:211], 0
	v_mfma_f32_16x16x32_bf16 v[20:23], v[172:175], v[212:215], v[20:23]
	v_mfma_f32_16x16x32_bf16 v[12:15], v[176:179], v[208:211], 0
	v_mfma_f32_16x16x32_bf16 v[12:15], v[180:183], v[212:215], v[12:15]
	v_mfma_f32_16x16x32_bf16 v[8:11], v[168:171], v[216:219], 0
	v_mfma_f32_16x16x32_bf16 v[8:11], v[172:175], v[220:223], v[8:11]
	s_setprio 2
	s_barrier
	v_mfma_f32_16x16x32_bf16 v[4:7], v[176:179], v[216:219], 0
	v_mfma_f32_16x16x32_bf16 v[4:7], v[180:183], v[220:223], v[4:7]
	s_setprio 0
	s_add_i32 s27, 0, 0x18000
	v_add_u32_e32 v158, s27, v145
	s_add_i32 s65, 0, 0x1c000
	ds_read_b128 v[140:143], v158
	ds_read_b128 v[148:151], v158 offset:1024
	ds_read_b128 v[152:155], v158 offset:2048
	ds_read_b128 v[164:167], v158 offset:3072
	v_add_u32_e32 v158, s65, v145
	ds_read_b128 v[168:171], v158
	ds_read_b128 v[172:175], v158 offset:1024
	ds_read_b128 v[176:179], v158 offset:2048
	ds_read_b128 v[180:183], v158 offset:3072
	s_add_u32 s30, s42, 0x80000
	s_addc_u32 s31, s43, 0
	s_mov_b32 m0, s60
	v_lshl_add_u64 v[228:229], s[30:31], 0, v[134:135]
	ds_read_b128 v[184:187], v147 offset:32768
	ds_read_b128 v[188:191], v147 offset:33792
	ds_read_b128 v[192:195], v147 offset:34816
	ds_read_b128 v[204:207], v147 offset:35840
	ds_read_b128 v[208:211], v147 offset:36864
	ds_read_b128 v[212:215], v147 offset:37888
	ds_read_b128 v[216:219], v147 offset:38912
	ds_read_b128 v[220:223], v147 offset:39936
	global_load_lds_dwordx4 v[228:229], off
	v_lshl_add_u64 v[228:229], s[30:31], 0, v[132:133]
	s_mov_b32 m0, s61
	s_nop 0
	global_load_lds_dwordx4 v[228:229], off
	s_waitcnt vmcnt(8)
	s_waitcnt lgkmcnt(0)
	s_barrier
	s_setprio 1
	s_waitcnt lgkmcnt(0)
	v_mfma_f32_16x16x32_bf16 v[128:131], v[140:143], v[184:187], v[128:131]
	v_mfma_f32_16x16x32_bf16 v[128:131], v[148:151], v[188:191], v[128:131]
	v_mfma_f32_16x16x32_bf16 v[124:127], v[152:155], v[184:187], v[124:127]
	v_mfma_f32_16x16x32_bf16 v[124:127], v[164:167], v[188:191], v[124:127]
	v_mfma_f32_16x16x32_bf16 v[120:123], v[140:143], v[192:195], v[120:123]
	v_mfma_f32_16x16x32_bf16 v[120:123], v[148:151], v[204:207], v[120:123]
	v_mfma_f32_16x16x32_bf16 v[112:115], v[152:155], v[192:195], v[112:115]
	v_mfma_f32_16x16x32_bf16 v[112:115], v[164:167], v[204:207], v[112:115]
	v_mfma_f32_16x16x32_bf16 v[104:107], v[140:143], v[208:211], v[104:107]
	v_mfma_f32_16x16x32_bf16 v[104:107], v[148:151], v[212:215], v[104:107]
	v_mfma_f32_16x16x32_bf16 v[96:99], v[152:155], v[208:211], v[96:99]
	v_mfma_f32_16x16x32_bf16 v[96:99], v[164:167], v[212:215], v[96:99]
	v_mfma_f32_16x16x32_bf16 v[88:91], v[140:143], v[216:219], v[88:91]
	v_mfma_f32_16x16x32_bf16 v[88:91], v[148:151], v[220:223], v[88:91]
	v_mfma_f32_16x16x32_bf16 v[80:83], v[152:155], v[216:219], v[80:83]
	v_mfma_f32_16x16x32_bf16 v[80:83], v[164:167], v[220:223], v[80:83]
	s_setprio 0
	s_setprio 1
	v_mfma_f32_16x16x32_bf16 v[116:119], v[168:171], v[184:187], v[116:119]
	v_mfma_f32_16x16x32_bf16 v[116:119], v[172:175], v[188:191], v[116:119]
	v_mfma_f32_16x16x32_bf16 v[108:111], v[176:179], v[184:187], v[108:111]
	v_mfma_f32_16x16x32_bf16 v[108:111], v[180:183], v[188:191], v[108:111]
	v_mfma_f32_16x16x32_bf16 v[100:103], v[168:171], v[192:195], v[100:103]
	v_mfma_f32_16x16x32_bf16 v[100:103], v[172:175], v[204:207], v[100:103]
	v_mfma_f32_16x16x32_bf16 v[92:95], v[176:179], v[192:195], v[92:95]
	v_mfma_f32_16x16x32_bf16 v[92:95], v[180:183], v[204:207], v[92:95]
	v_mfma_f32_16x16x32_bf16 v[84:87], v[168:171], v[208:211], v[84:87]
	v_mfma_f32_16x16x32_bf16 v[84:87], v[172:175], v[212:215], v[84:87]
	v_mfma_f32_16x16x32_bf16 v[76:79], v[176:179], v[208:211], v[76:79]
	v_mfma_f32_16x16x32_bf16 v[76:79], v[180:183], v[212:215], v[76:79]
	v_mfma_f32_16x16x32_bf16 v[72:75], v[168:171], v[216:219], v[72:75]
	v_mfma_f32_16x16x32_bf16 v[72:75], v[172:175], v[220:223], v[72:75]
	s_setprio 2
	s_barrier
; #define PG8_STAGE(bufoff, gbase, voff) do { _Pragma("unroll") for (int _i = 0; _i < 2; ++_i) \
;         __builtin_amdgcn_global_load_lds((const unsigned*)((const char*)(gbase) + (voff)[_i]), (LAS unsigned*)(lds + (bufoff) + ldsw + _i * 8192), 16, 0, 0); } while (0)
; #define PG8_LDA(dst, b, h) do { _Pragma("unroll") for (int m = 0; m < 4; ++m) _Pragma("unroll") for (int k = 0; k < 2; ++k) dst[m][k] = *(const LAS bf16x8*)(lds + PG8_SA(b, h) + aoff + m * 2048 + k * 1024); } while (0)
; #define PG8_LDB(dst, b, h) do { _Pragma("unroll") for (int n = 0; n < 2; ++n) _Pragma("unroll") for (int k = 0; k < 2; ++k) dst[n][k] = *(const LAS bf16x8*)(lds + PG8_SB(b, h) + boff + n * 2048 + k * 1024); } while (0)
; #define PG8_WAIT_V(n) asm volatile("s_waitcnt vmcnt(" #n ")" ::: "memory")
; #define PG8_WAIT_L(n) asm volatile("s_waitcnt lgkmcnt(" #n ")" ::: "memory")
; template <class Epi, class Sched, bool ALIGN_EPI = true>
; __device__ __forceinline__ void gemm_phase(LAS unsigned char* lds, const Gemm g, const Sched& S, const Epi& E) {
;     ...
;             const bool last = (t == nt - 2);
;             const char* a1 = cA + (size_t)(t + 1) * kstep;
;             const char* a2 = last ? nA : cA + (size_t)(t + 2) * kstep; const char* b2 = last ? nB : cB + (size_t)(t + 2) * kstep;
;             const char* a3 = a2 + kstep; const char* b3 = b2 + kstep;
;             PG8_LDB(B0, 0, 0); PG8_LDB(B1, 0, 1); PG8_SCHED; PG8_LDA(At, 0, 0); PG8_STAGE(PG8_SA(1, 1), a1 + hA, voffA);
;             PG8_WAIT_V(8); PG8_WAIT_L(0); PG8_BAR; PG8_MMA(0, 0, At, B0); PG8_MMA(0, 1, At, B1); PG8_BAR; PG8_SCHED;
;             PG8_LDA(At, 0, 1); PG8_STAGE(PG8_SB(0, 0), b2, voffB); PG8_STAGE(PG8_SB(0, 1), b2 + hB, voffB); PG8_STAGE(PG8_SA(0, 0), a2, voffA);
;             PG8_WAIT_V(8); PG8_WAIT_L(0); PG8_BAR; PG8_MMA(1, 0, At, B0); PG8_MMA(1, 1, At, B1); PG8_BAR; PG8_SCHED;
;             PG8_LDB(B0, 1, 0); PG8_LDB(B1, 1, 1); PG8_SCHED; PG8_LDA(At, 1, 0); PG8_STAGE(PG8_SA(0, 1), a2 + hA, voffA);
;             PG8_WAIT_V(8); PG8_WAIT_L(0); PG8_BAR; PG8_MMA(0, 0, At, B0); PG8_MMA(0, 1, At, B1); PG8_BAR; PG8_SCHED;
;             PG8_LDA(At, 1, 1); PG8_STAGE(PG8_SB(1, 0), b3, voffB); PG8_STAGE(PG8_SB(1, 1), b3 + hB, voffB); PG8_STAGE(PG8_SA(1, 0), a3, voffA);
;             PG8_WAIT_V(8); PG8_WAIT_L(0); PG8_BAR; PG8_MMA(1, 0, At, B0); PG8_MMA(1, 1, At, B1); PG8_BAR; PG8_SCHED;
	v_mfma_f32_16x16x32_bf16 v[68:71], v[176:179], v[216:219], v[68:71]
	v_mfma_f32_16x16x32_bf16 v[68:71], v[180:183], v[220:223], v[68:71]
	s_setprio 0
	s_add_i32 s27, s27, s53
	v_lshl_add_u64 v[156:157], v[156:157], 0, s[86:87]
	s_mov_b32 m0, s27
	ds_read_b128 v[184:187], v147 offset:49152
	ds_read_b128 v[188:191], v147 offset:50176
	ds_read_b128 v[192:195], v147 offset:51200
	ds_read_b128 v[204:207], v147 offset:52224
	ds_read_b128 v[208:211], v147 offset:53248
	ds_read_b128 v[212:215], v147 offset:54272
	ds_read_b128 v[216:219], v147 offset:55296
	ds_read_b128 v[220:223], v147 offset:56320
	global_load_lds_dwordx4 v[156:157], off
	s_add_i32 m0, s27, 0x2000
	s_add_u32 s30, s40, 0x80080
	v_lshl_add_u64 v[156:157], v[196:197], 0, s[86:87]
	s_addc_u32 s31, s41, 0
	s_add_i32 s27, s65, s53
	global_load_lds_dwordx4 v[156:157], off
	v_lshl_add_u64 v[156:157], s[30:31], 0, v[2:3]
	s_mov_b32 m0, s27
	s_nop 0
	global_load_lds_dwordx4 v[156:157], off
	v_lshl_add_u64 v[156:157], s[30:31], 0, v[0:1]
	s_add_i32 m0, s27, 0x2000
	s_nop 0
	global_load_lds_dwordx4 v[156:157], off
	v_lshl_add_u64 v[156:157], v[224:225], 0, s[86:87]
	s_mov_b32 m0, s62
	s_nop 0
	global_load_lds_dwordx4 v[156:157], off
	v_lshl_add_u64 v[156:157], v[226:227], 0, s[86:87]
	s_mov_b32 m0, s63
	s_nop 0
	global_load_lds_dwordx4 v[156:157], off
	s_waitcnt vmcnt(8)
	s_waitcnt lgkmcnt(0)
	s_barrier
	s_setprio 1
	s_waitcnt lgkmcnt(0)
	v_mfma_f32_16x16x32_bf16 v[64:67], v[140:143], v[184:187], v[64:67]
	v_mfma_f32_16x16x32_bf16 v[64:67], v[148:151], v[188:191], v[64:67]
	s_add_i32 s26, s26, 2
	s_add_u32 s38, s38, 0x100
	v_mfma_f32_16x16x32_bf16 v[60:63], v[152:155], v[184:187], v[60:63]
	v_mfma_f32_16x16x32_bf16 v[60:63], v[164:167], v[188:191], v[60:63]
	s_addc_u32 s39, s39, 0
	s_add_u32 s24, s24, 0x100
	v_mfma_f32_16x16x32_bf16 v[56:59], v[140:143], v[192:195], v[56:59]
	v_mfma_f32_16x16x32_bf16 v[56:59], v[148:151], v[204:207], v[56:59]
	s_addc_u32 s25, s25, 0
	s_add_u32 s27, s38, 0xfff80080
	v_mfma_f32_16x16x32_bf16 v[48:51], v[152:155], v[192:195], v[48:51]
	v_mfma_f32_16x16x32_bf16 v[48:51], v[164:167], v[204:207], v[48:51]
	s_addc_u32 s30, s39, -1
	s_add_i32 s31, 0, 0x10000
	v_mfma_f32_16x16x32_bf16 v[40:43], v[140:143], v[208:211], v[40:43]
	v_mfma_f32_16x16x32_bf16 v[40:43], v[148:151], v[212:215], v[40:43]
	s_cmp_eq_u32 s26, 28
	s_cselect_b32 s43, s11, s30
	v_mfma_f32_16x16x32_bf16 v[32:35], v[152:155], v[208:211], v[32:35]
	v_mfma_f32_16x16x32_bf16 v[32:35], v[164:167], v[212:215], v[32:35]
	s_cselect_b32 s42, s18, s27
	s_cselect_b32 s41, s9, s25
	v_mfma_f32_16x16x32_bf16 v[24:27], v[140:143], v[216:219], v[24:27]
	v_mfma_f32_16x16x32_bf16 v[24:27], v[148:151], v[220:223], v[24:27]
	s_cselect_b32 s40, s19, s24
	s_add_i32 s27, 0, 0x14000
	v_mfma_f32_16x16x32_bf16 v[16:19], v[152:155], v[216:219], v[16:19]
	v_mfma_f32_16x16x32_bf16 v[16:19], v[164:167], v[220:223], v[16:19]
	s_setprio 0
	s_setprio 1
	v_mfma_f32_16x16x32_bf16 v[52:55], v[168:171], v[184:187], v[52:55]
	v_mfma_f32_16x16x32_bf16 v[52:55], v[172:175], v[188:191], v[52:55]
	v_mfma_f32_16x16x32_bf16 v[44:47], v[176:179], v[184:187], v[44:47]
	v_mfma_f32_16x16x32_bf16 v[44:47], v[180:183], v[188:191], v[44:47]
	v_mfma_f32_16x16x32_bf16 v[36:39], v[168:171], v[192:195], v[36:39]
	v_mfma_f32_16x16x32_bf16 v[36:39], v[172:175], v[204:207], v[36:39]
	v_mfma_f32_16x16x32_bf16 v[28:31], v[176:179], v[192:195], v[28:31]
	v_mfma_f32_16x16x32_bf16 v[28:31], v[180:183], v[204:207], v[28:31]
	v_mfma_f32_16x16x32_bf16 v[20:23], v[168:171], v[208:211], v[20:23]
	v_mfma_f32_16x16x32_bf16 v[20:23], v[172:175], v[212:215], v[20:23]
	v_mfma_f32_16x16x32_bf16 v[12:15], v[176:179], v[208:211], v[12:15]
	v_mfma_f32_16x16x32_bf16 v[12:15], v[180:183], v[212:215], v[12:15]
	v_mfma_f32_16x16x32_bf16 v[8:11], v[168:171], v[216:219], v[8:11]
	v_mfma_f32_16x16x32_bf16 v[8:11], v[172:175], v[220:223], v[8:11]
	s_setprio 2
	s_barrier
	v_mfma_f32_16x16x32_bf16 v[4:7], v[176:179], v[216:219], v[4:7]
	v_mfma_f32_16x16x32_bf16 v[4:7], v[180:183], v[220:223], v[4:7]
	s_setprio 0
	s_cmp_gt_u32 s26, 29
	s_cbranch_scc1 .Lpeel_exit_218
.LBB0_218:
	v_add_u32_e32 v156, s31, v145
	ds_read_b128 v[140:143], v156
	ds_read_b128 v[148:151], v156 offset:1024
	ds_read_b128 v[152:155], v156 offset:2048
	ds_read_b128 v[164:167], v156 offset:3072
	v_add_u32_e32 v156, s27, v145
	ds_read_b128 v[168:171], v156
	ds_read_b128 v[172:175], v156 offset:1024
	ds_read_b128 v[176:179], v156 offset:2048
	ds_read_b128 v[180:183], v156 offset:3072
	v_lshl_add_u64 v[156:157], s[38:39], 0, v[136:137]
	s_add_i32 m0, s58, 0xc000
	ds_read_b128 v[184:187], v147
	ds_read_b128 v[188:191], v147 offset:1024
	ds_read_b128 v[192:195], v147 offset:2048
	ds_read_b128 v[204:207], v147 offset:3072
	ds_read_b128 v[208:211], v147 offset:4096
	ds_read_b128 v[212:215], v147 offset:5120
	ds_read_b128 v[216:219], v147 offset:6144
	ds_read_b128 v[220:223], v147 offset:7168
	global_load_lds_dwordx4 v[156:157], off
	v_lshl_add_u64 v[156:157], s[38:39], 0, v[138:139]
	s_add_i32 m0, s58, 0xe000
	s_nop 0
	global_load_lds_dwordx4 v[156:157], off
	s_waitcnt vmcnt(8)
	s_waitcnt lgkmcnt(0)
	s_barrier
; #define PG8_STAGE(bufoff, gbase, voff) do { _Pragma("unroll") for (int _i = 0; _i < 2; ++_i) \
;         __builtin_amdgcn_global_load_lds((const unsigned*)((const char*)(gbase) + (voff)[_i]), (LAS unsigned*)(lds + (bufoff) + ldsw + _i * 8192), 16, 0, 0); } while (0)
; #define PG8_LDA(dst, b, h) do { _Pragma("unroll") for (int m = 0; m < 4; ++m) _Pragma("unroll") for (int k = 0; k < 2; ++k) dst[m][k] = *(const LAS bf16x8*)(lds + PG8_SA(b, h) + aoff + m * 2048 + k * 1024); } while (0)
; #define PG8_MMA(ai, bj, At, Bt) do { __builtin_amdgcn_s_setprio(1); _Pragma("unroll") for (int m = 0; m < 4; ++m) _Pragma("unroll") for (int n = 0; n < 2; ++n) _Pragma("unroll") for (int k = 0; k < 2; ++k) \
;         acc[ai][bj][m][n] = __builtin_amdgcn_mfma_f32_16x16x32_bf16(Bt[n][k], At[m][k], acc[ai][bj][m][n], 0, 0, 0); __builtin_amdgcn_s_setprio(0); } while (0)
; #define PG8_WAIT_V(n) asm volatile("s_waitcnt vmcnt(" #n ")" ::: "memory")
; #define PG8_WAIT_L(n) asm volatile("s_waitcnt lgkmcnt(" #n ")" ::: "memory")
; #define PG8_BAR __builtin_amdgcn_s_barrier()
; #define PG8_SCHED __builtin_amdgcn_sched_barrier(0)
; template <class Epi, class Sched, bool ALIGN_EPI = true>
; __device__ __forceinline__ void gemm_phase(LAS unsigned char* lds, const Gemm g, const Sched& S, const Epi& E) {
;     ...
;             PG8_WAIT_V(8); PG8_WAIT_L(0); PG8_BAR; PG8_MMA(0, 0, At, B0); PG8_MMA(0, 1, At, B1); PG8_BAR; PG8_SCHED;
;             PG8_LDA(At, 0, 1); PG8_STAGE(PG8_SB(0, 0), b2, voffB); PG8_STAGE(PG8_SB(0, 1), b2 + hB, voffB); PG8_STAGE(PG8_SA(0, 0), a2, voffA);
;             PG8_WAIT_V(8); PG8_WAIT_L(0); PG8_BAR; PG8_MMA(1, 0, At, B0); PG8_MMA(1, 1, At, B1); PG8_BAR; PG8_SCHED;
	s_setprio 1
	s_waitcnt lgkmcnt(0)
	v_mfma_f32_16x16x32_bf16 v[128:131], v[140:143], v[184:187], v[128:131]
	v_mfma_f32_16x16x32_bf16 v[128:131], v[148:151], v[188:191], v[128:131]
	v_mfma_f32_16x16x32_bf16 v[124:127], v[152:155], v[184:187], v[124:127]
	v_mfma_f32_16x16x32_bf16 v[124:127], v[164:167], v[188:191], v[124:127]
	v_mfma_f32_16x16x32_bf16 v[120:123], v[140:143], v[192:195], v[120:123]
	v_mfma_f32_16x16x32_bf16 v[120:123], v[148:151], v[204:207], v[120:123]
	v_mfma_f32_16x16x32_bf16 v[112:115], v[152:155], v[192:195], v[112:115]
	v_mfma_f32_16x16x32_bf16 v[112:115], v[164:167], v[204:207], v[112:115]
	v_mfma_f32_16x16x32_bf16 v[104:107], v[140:143], v[208:211], v[104:107]
	v_mfma_f32_16x16x32_bf16 v[104:107], v[148:151], v[212:215], v[104:107]
	v_mfma_f32_16x16x32_bf16 v[96:99], v[152:155], v[208:211], v[96:99]
	v_mfma_f32_16x16x32_bf16 v[96:99], v[164:167], v[212:215], v[96:99]
	v_mfma_f32_16x16x32_bf16 v[88:91], v[140:143], v[216:219], v[88:91]
	v_mfma_f32_16x16x32_bf16 v[88:91], v[148:151], v[220:223], v[88:91]
	v_mfma_f32_16x16x32_bf16 v[80:83], v[152:155], v[216:219], v[80:83]
	v_mfma_f32_16x16x32_bf16 v[80:83], v[164:167], v[220:223], v[80:83]
	s_setprio 0
	s_setprio 1
	v_mfma_f32_16x16x32_bf16 v[116:119], v[168:171], v[184:187], v[116:119]
	v_mfma_f32_16x16x32_bf16 v[116:119], v[172:175], v[188:191], v[116:119]
	v_mfma_f32_16x16x32_bf16 v[108:111], v[176:179], v[184:187], v[108:111]
	v_mfma_f32_16x16x32_bf16 v[108:111], v[180:183], v[188:191], v[108:111]
	v_mfma_f32_16x16x32_bf16 v[100:103], v[168:171], v[192:195], v[100:103]
	v_mfma_f32_16x16x32_bf16 v[100:103], v[172:175], v[204:207], v[100:103]
	v_mfma_f32_16x16x32_bf16 v[92:95], v[176:179], v[192:195], v[92:95]
	v_mfma_f32_16x16x32_bf16 v[92:95], v[180:183], v[204:207], v[92:95]
	v_mfma_f32_16x16x32_bf16 v[84:87], v[168:171], v[208:211], v[84:87]
	v_mfma_f32_16x16x32_bf16 v[84:87], v[172:175], v[212:215], v[84:87]
	v_mfma_f32_16x16x32_bf16 v[76:79], v[176:179], v[208:211], v[76:79]
	v_mfma_f32_16x16x32_bf16 v[76:79], v[180:183], v[212:215], v[76:79]
	v_mfma_f32_16x16x32_bf16 v[72:75], v[168:171], v[216:219], v[72:75]
	v_mfma_f32_16x16x32_bf16 v[72:75], v[172:175], v[220:223], v[72:75]
	s_setprio 2
	s_barrier
	v_mfma_f32_16x16x32_bf16 v[68:71], v[176:179], v[216:219], v[68:71]
	v_mfma_f32_16x16x32_bf16 v[68:71], v[180:183], v[220:223], v[68:71]
	s_setprio 0
	s_add_i32 s30, s31, s53
	v_lshl_add_u64 v[156:157], s[40:41], 0, v[2:3]
	s_mov_b32 m0, s30
	ds_read_b128 v[184:187], v147 offset:16384
	ds_read_b128 v[188:191], v147 offset:17408
	ds_read_b128 v[192:195], v147 offset:18432
	ds_read_b128 v[204:207], v147 offset:19456
	ds_read_b128 v[208:211], v147 offset:20480
	ds_read_b128 v[212:215], v147 offset:21504
	ds_read_b128 v[216:219], v147 offset:22528
	ds_read_b128 v[220:223], v147 offset:23552
	global_load_lds_dwordx4 v[156:157], off
	s_add_i32 m0, s30, 0x2000
	s_add_u32 s30, s40, 0x80000
	v_lshl_add_u64 v[196:197], s[40:41], 0, v[0:1]
	s_addc_u32 s31, s41, 0
	s_add_i32 s27, s27, s53
	global_load_lds_dwordx4 v[196:197], off
	v_lshl_add_u64 v[224:225], s[30:31], 0, v[2:3]
	s_mov_b32 m0, s27
	v_lshl_add_u64 v[226:227], s[42:43], 0, v[132:133]
	global_load_lds_dwordx4 v[224:225], off
	v_lshl_add_u64 v[224:225], s[30:31], 0, v[0:1]
	s_add_i32 m0, s27, 0x2000
	s_nop 0
	global_load_lds_dwordx4 v[224:225], off
	v_lshl_add_u64 v[224:225], s[42:43], 0, v[134:135]
	s_mov_b32 m0, s58
	s_nop 0
	global_load_lds_dwordx4 v[224:225], off
	s_mov_b32 m0, s59
	s_nop 0
	global_load_lds_dwordx4 v[226:227], off
	s_waitcnt vmcnt(8)
	s_waitcnt lgkmcnt(0)
	s_barrier
	s_setprio 1
	s_waitcnt lgkmcnt(0)
	v_mfma_f32_16x16x32_bf16 v[64:67], v[140:143], v[184:187], v[64:67]
	v_mfma_f32_16x16x32_bf16 v[64:67], v[148:151], v[188:191], v[64:67]
	v_mfma_f32_16x16x32_bf16 v[60:63], v[152:155], v[184:187], v[60:63]
	v_mfma_f32_16x16x32_bf16 v[60:63], v[164:167], v[188:191], v[60:63]
	v_mfma_f32_16x16x32_bf16 v[56:59], v[140:143], v[192:195], v[56:59]
	v_mfma_f32_16x16x32_bf16 v[56:59], v[148:151], v[204:207], v[56:59]
	v_mfma_f32_16x16x32_bf16 v[48:51], v[152:155], v[192:195], v[48:51]
	v_mfma_f32_16x16x32_bf16 v[48:51], v[164:167], v[204:207], v[48:51]
	v_mfma_f32_16x16x32_bf16 v[40:43], v[140:143], v[208:211], v[40:43]
	v_mfma_f32_16x16x32_bf16 v[40:43], v[148:151], v[212:215], v[40:43]
	v_mfma_f32_16x16x32_bf16 v[32:35], v[152:155], v[208:211], v[32:35]
	v_mfma_f32_16x16x32_bf16 v[32:35], v[164:167], v[212:215], v[32:35]
	v_mfma_f32_16x16x32_bf16 v[24:27], v[140:143], v[216:219], v[24:27]
	v_mfma_f32_16x16x32_bf16 v[24:27], v[148:151], v[220:223], v[24:27]
	v_mfma_f32_16x16x32_bf16 v[16:19], v[152:155], v[216:219], v[16:19]
	v_mfma_f32_16x16x32_bf16 v[16:19], v[164:167], v[220:223], v[16:19]
	s_setprio 0
	s_setprio 1
	v_mfma_f32_16x16x32_bf16 v[52:55], v[168:171], v[184:187], v[52:55]
	v_mfma_f32_16x16x32_bf16 v[52:55], v[172:175], v[188:191], v[52:55]
	v_mfma_f32_16x16x32_bf16 v[44:47], v[176:179], v[184:187], v[44:47]
	v_mfma_f32_16x16x32_bf16 v[44:47], v[180:183], v[188:191], v[44:47]
	v_mfma_f32_16x16x32_bf16 v[36:39], v[168:171], v[192:195], v[36:39]
	v_mfma_f32_16x16x32_bf16 v[36:39], v[172:175], v[204:207], v[36:39]
	v_mfma_f32_16x16x32_bf16 v[28:31], v[176:179], v[192:195], v[28:31]
	v_mfma_f32_16x16x32_bf16 v[28:31], v[180:183], v[204:207], v[28:31]
	v_mfma_f32_16x16x32_bf16 v[20:23], v[168:171], v[208:211], v[20:23]
	v_mfma_f32_16x16x32_bf16 v[20:23], v[172:175], v[212:215], v[20:23]
	v_mfma_f32_16x16x32_bf16 v[12:15], v[176:179], v[208:211], v[12:15]
	v_mfma_f32_16x16x32_bf16 v[12:15], v[180:183], v[212:215], v[12:15]
	v_mfma_f32_16x16x32_bf16 v[8:11], v[168:171], v[216:219], v[8:11]
	v_mfma_f32_16x16x32_bf16 v[8:11], v[172:175], v[220:223], v[8:11]
	s_setprio 2
	s_barrier
; #define PG8_STAGE(bufoff, gbase, voff) do { _Pragma("unroll") for (int _i = 0; _i < 2; ++_i) \
;         __builtin_amdgcn_global_load_lds((const unsigned*)((const char*)(gbase) + (voff)[_i]), (LAS unsigned*)(lds + (bufoff) + ldsw + _i * 8192), 16, 0, 0); } while (0)
; #define PG8_LDA(dst, b, h) do { _Pragma("unroll") for (int m = 0; m < 4; ++m) _Pragma("unroll") for (int k = 0; k < 2; ++k) dst[m][k] = *(const LAS bf16x8*)(lds + PG8_SA(b, h) + aoff + m * 2048 + k * 1024); } while (0)
; #define PG8_LDB(dst, b, h) do { _Pragma("unroll") for (int n = 0; n < 2; ++n) _Pragma("unroll") for (int k = 0; k < 2; ++k) dst[n][k] = *(const LAS bf16x8*)(lds + PG8_SB(b, h) + boff + n * 2048 + k * 1024); } while (0)
; #define PG8_MMA(ai, bj, At, Bt) do { __builtin_amdgcn_s_setprio(1); _Pragma("unroll") for (int m = 0; m < 4; ++m) _Pragma("unroll") for (int n = 0; n < 2; ++n) _Pragma("unroll") for (int k = 0; k < 2; ++k) \
;         acc[ai][bj][m][n] = __builtin_amdgcn_mfma_f32_16x16x32_bf16(Bt[n][k], At[m][k], acc[ai][bj][m][n], 0, 0, 0); __builtin_amdgcn_s_setprio(0); } while (0)
; #define PG8_WAIT_V(n) asm volatile("s_waitcnt vmcnt(" #n ")" ::: "memory")
; #define PG8_WAIT_L(n) asm volatile("s_waitcnt lgkmcnt(" #n ")" ::: "memory")
; #define PG8_BAR __builtin_amdgcn_s_barrier()
; #define PG8_SCHED __builtin_amdgcn_sched_barrier(0)
; template <class Epi, class Sched, bool ALIGN_EPI = true>
; __device__ __forceinline__ void gemm_phase(LAS unsigned char* lds, const Gemm g, const Sched& S, const Epi& E) {
;     ...
;             PG8_WAIT_V(8); PG8_WAIT_L(0); PG8_BAR; PG8_MMA(1, 0, At, B0); PG8_MMA(1, 1, At, B1); PG8_BAR; PG8_SCHED;
;             PG8_LDB(B0, 1, 0); PG8_LDB(B1, 1, 1); PG8_SCHED; PG8_LDA(At, 1, 0); PG8_STAGE(PG8_SA(0, 1), a2 + hA, voffA);
;             PG8_WAIT_V(8); PG8_WAIT_L(0); PG8_BAR; PG8_MMA(0, 0, At, B0); PG8_MMA(0, 1, At, B1); PG8_BAR; PG8_SCHED;
	v_mfma_f32_16x16x32_bf16 v[4:7], v[176:179], v[216:219], v[4:7]
	v_mfma_f32_16x16x32_bf16 v[4:7], v[180:183], v[220:223], v[4:7]
	s_setprio 0
	s_add_i32 s27, 0, 0x18000
	v_add_u32_e32 v158, s27, v145
	s_add_i32 s65, 0, 0x1c000
	ds_read_b128 v[140:143], v158
	ds_read_b128 v[148:151], v158 offset:1024
	ds_read_b128 v[152:155], v158 offset:2048
	ds_read_b128 v[164:167], v158 offset:3072
	v_add_u32_e32 v158, s65, v145
	ds_read_b128 v[168:171], v158
	ds_read_b128 v[172:175], v158 offset:1024
	ds_read_b128 v[176:179], v158 offset:2048
	ds_read_b128 v[180:183], v158 offset:3072
	s_add_u32 s30, s42, 0x80000
	s_addc_u32 s31, s43, 0
	s_mov_b32 m0, s60
	v_lshl_add_u64 v[228:229], s[30:31], 0, v[134:135]
	ds_read_b128 v[184:187], v147 offset:32768
	ds_read_b128 v[188:191], v147 offset:33792
	ds_read_b128 v[192:195], v147 offset:34816
	ds_read_b128 v[204:207], v147 offset:35840
	ds_read_b128 v[208:211], v147 offset:36864
	ds_read_b128 v[212:215], v147 offset:37888
	ds_read_b128 v[216:219], v147 offset:38912
	ds_read_b128 v[220:223], v147 offset:39936
	global_load_lds_dwordx4 v[228:229], off
	v_lshl_add_u64 v[228:229], s[30:31], 0, v[132:133]
	s_mov_b32 m0, s61
	s_nop 0
	global_load_lds_dwordx4 v[228:229], off
	s_waitcnt vmcnt(8)
	s_waitcnt lgkmcnt(0)
	s_barrier
	s_setprio 1
	s_waitcnt lgkmcnt(0)
	v_mfma_f32_16x16x32_bf16 v[128:131], v[140:143], v[184:187], v[128:131]
	v_mfma_f32_16x16x32_bf16 v[128:131], v[148:151], v[188:191], v[128:131]
	v_mfma_f32_16x16x32_bf16 v[124:127], v[152:155], v[184:187], v[124:127]
	v_mfma_f32_16x16x32_bf16 v[124:127], v[164:167], v[188:191], v[124:127]
	v_mfma_f32_16x16x32_bf16 v[120:123], v[140:143], v[192:195], v[120:123]
	v_mfma_f32_16x16x32_bf16 v[120:123], v[148:151], v[204:207], v[120:123]
	v_mfma_f32_16x16x32_bf16 v[112:115], v[152:155], v[192:195], v[112:115]
	v_mfma_f32_16x16x32_bf16 v[112:115], v[164:167], v[204:207], v[112:115]
	v_mfma_f32_16x16x32_bf16 v[104:107], v[140:143], v[208:211], v[104:107]
	v_mfma_f32_16x16x32_bf16 v[104:107], v[148:151], v[212:215], v[104:107]
	v_mfma_f32_16x16x32_bf16 v[96:99], v[152:155], v[208:211], v[96:99]
	v_mfma_f32_16x16x32_bf16 v[96:99], v[164:167], v[212:215], v[96:99]
	v_mfma_f32_16x16x32_bf16 v[88:91], v[140:143], v[216:219], v[88:91]
	v_mfma_f32_16x16x32_bf16 v[88:91], v[148:151], v[220:223], v[88:91]
	v_mfma_f32_16x16x32_bf16 v[80:83], v[152:155], v[216:219], v[80:83]
	v_mfma_f32_16x16x32_bf16 v[80:83], v[164:167], v[220:223], v[80:83]
	s_setprio 0
	s_setprio 1
	v_mfma_f32_16x16x32_bf16 v[116:119], v[168:171], v[184:187], v[116:119]
	v_mfma_f32_16x16x32_bf16 v[116:119], v[172:175], v[188:191], v[116:119]
	v_mfma_f32_16x16x32_bf16 v[108:111], v[176:179], v[184:187], v[108:111]
	v_mfma_f32_16x16x32_bf16 v[108:111], v[180:183], v[188:191], v[108:111]
	v_mfma_f32_16x16x32_bf16 v[100:103], v[168:171], v[192:195], v[100:103]
	v_mfma_f32_16x16x32_bf16 v[100:103], v[172:175], v[204:207], v[100:103]
	v_mfma_f32_16x16x32_bf16 v[92:95], v[176:179], v[192:195], v[92:95]
	v_mfma_f32_16x16x32_bf16 v[92:95], v[180:183], v[204:207], v[92:95]
	v_mfma_f32_16x16x32_bf16 v[84:87], v[168:171], v[208:211], v[84:87]
	v_mfma_f32_16x16x32_bf16 v[84:87], v[172:175], v[212:215], v[84:87]
	v_mfma_f32_16x16x32_bf16 v[76:79], v[176:179], v[208:211], v[76:79]
	v_mfma_f32_16x16x32_bf16 v[76:79], v[180:183], v[212:215], v[76:79]
	v_mfma_f32_16x16x32_bf16 v[72:75], v[168:171], v[216:219], v[72:75]
	v_mfma_f32_16x16x32_bf16 v[72:75], v[172:175], v[220:223], v[72:75]
	s_setprio 2
	s_barrier
; #define PG8_STAGE(bufoff, gbase, voff) do { _Pragma("unroll") for (int _i = 0; _i < 2; ++_i) \
;         __builtin_amdgcn_global_load_lds((const unsigned*)((const char*)(gbase) + (voff)[_i]), (LAS unsigned*)(lds + (bufoff) + ldsw + _i * 8192), 16, 0, 0); } while (0)
; #define PG8_LDA(dst, b, h) do { _Pragma("unroll") for (int m = 0; m < 4; ++m) _Pragma("unroll") for (int k = 0; k < 2; ++k) dst[m][k] = *(const LAS bf16x8*)(lds + PG8_SA(b, h) + aoff + m * 2048 + k * 1024); } while (0)
; #define PG8_MMA(ai, bj, At, Bt) do { __builtin_amdgcn_s_setprio(1); _Pragma("unroll") for (int m = 0; m < 4; ++m) _Pragma("unroll") for (int n = 0; n < 2; ++n) _Pragma("unroll") for (int k = 0; k < 2; ++k) \
;         acc[ai][bj][m][n] = __builtin_amdgcn_mfma_f32_16x16x32_bf16(Bt[n][k], At[m][k], acc[ai][bj][m][n], 0, 0, 0); __builtin_amdgcn_s_setprio(0); } while (0)
; #define PG8_WAIT_V(n) asm volatile("s_waitcnt vmcnt(" #n ")" ::: "memory")
; #define PG8_WAIT_L(n) asm volatile("s_waitcnt lgkmcnt(" #n ")" ::: "memory")
; #define PG8_BAR __builtin_amdgcn_s_barrier()
; #define PG8_SCHED __builtin_amdgcn_sched_barrier(0)
; template <class Epi, class Sched, bool ALIGN_EPI = true>
; __device__ __forceinline__ void gemm_phase(LAS unsigned char* lds, const Gemm g, const Sched& S, const Epi& E) {
;     ...
;             const bool last = (t == nt - 2);
;             const char* a1 = cA + (size_t)(t + 1) * kstep;
;             const char* a2 = last ? nA : cA + (size_t)(t + 2) * kstep; const char* b2 = last ? nB : cB + (size_t)(t + 2) * kstep;
;             const char* a3 = a2 + kstep; const char* b3 = b2 + kstep;
;     ...
;             PG8_WAIT_V(8); PG8_WAIT_L(0); PG8_BAR; PG8_MMA(0, 0, At, B0); PG8_MMA(0, 1, At, B1); PG8_BAR; PG8_SCHED;
;             PG8_LDA(At, 1, 1); PG8_STAGE(PG8_SB(1, 0), b3, voffB); PG8_STAGE(PG8_SB(1, 1), b3 + hB, voffB); PG8_STAGE(PG8_SA(1, 0), a3, voffA);
;             PG8_WAIT_V(8); PG8_WAIT_L(0); PG8_BAR; PG8_MMA(1, 0, At, B0); PG8_MMA(1, 1, At, B1); PG8_BAR; PG8_SCHED;
	v_mfma_f32_16x16x32_bf16 v[68:71], v[176:179], v[216:219], v[68:71]
	v_mfma_f32_16x16x32_bf16 v[68:71], v[180:183], v[220:223], v[68:71]
	s_setprio 0
	s_add_i32 s27, s27, s53
	v_lshl_add_u64 v[156:157], v[156:157], 0, s[86:87]
	s_mov_b32 m0, s27
	ds_read_b128 v[184:187], v147 offset:49152
	ds_read_b128 v[188:191], v147 offset:50176
	ds_read_b128 v[192:195], v147 offset:51200
	ds_read_b128 v[204:207], v147 offset:52224
	ds_read_b128 v[208:211], v147 offset:53248
	ds_read_b128 v[212:215], v147 offset:54272
	ds_read_b128 v[216:219], v147 offset:55296
	ds_read_b128 v[220:223], v147 offset:56320
	global_load_lds_dwordx4 v[156:157], off
	s_add_i32 m0, s27, 0x2000
	s_add_u32 s30, s40, 0x80080
	v_lshl_add_u64 v[156:157], v[196:197], 0, s[86:87]
	s_addc_u32 s31, s41, 0
	s_add_i32 s27, s65, s53
	global_load_lds_dwordx4 v[156:157], off
	v_lshl_add_u64 v[156:157], s[30:31], 0, v[2:3]
	s_mov_b32 m0, s27
	s_nop 0
	global_load_lds_dwordx4 v[156:157], off
	v_lshl_add_u64 v[156:157], s[30:31], 0, v[0:1]
	s_add_i32 m0, s27, 0x2000
	s_nop 0
	global_load_lds_dwordx4 v[156:157], off
	v_lshl_add_u64 v[156:157], v[224:225], 0, s[86:87]
	s_mov_b32 m0, s62
	s_nop 0
	global_load_lds_dwordx4 v[156:157], off
	v_lshl_add_u64 v[156:157], v[226:227], 0, s[86:87]
	s_mov_b32 m0, s63
	s_nop 0
	global_load_lds_dwordx4 v[156:157], off
	s_waitcnt vmcnt(8)
	s_waitcnt lgkmcnt(0)
	s_barrier
	s_setprio 1
	s_waitcnt lgkmcnt(0)
	v_mfma_f32_16x16x32_bf16 v[64:67], v[140:143], v[184:187], v[64:67]
	v_mfma_f32_16x16x32_bf16 v[64:67], v[148:151], v[188:191], v[64:67]
	s_add_i32 s26, s26, 2
	s_add_u32 s38, s38, 0x100
	v_mfma_f32_16x16x32_bf16 v[60:63], v[152:155], v[184:187], v[60:63]
	v_mfma_f32_16x16x32_bf16 v[60:63], v[164:167], v[188:191], v[60:63]
	s_addc_u32 s39, s39, 0
	s_add_u32 s24, s24, 0x100
	v_mfma_f32_16x16x32_bf16 v[56:59], v[140:143], v[192:195], v[56:59]
	v_mfma_f32_16x16x32_bf16 v[56:59], v[148:151], v[204:207], v[56:59]
	s_addc_u32 s25, s25, 0
	s_add_u32 s27, s38, 0xfff80080
	v_mfma_f32_16x16x32_bf16 v[48:51], v[152:155], v[192:195], v[48:51]
	v_mfma_f32_16x16x32_bf16 v[48:51], v[164:167], v[204:207], v[48:51]
	s_addc_u32 s30, s39, -1
	s_add_i32 s31, 0, 0x10000
	v_mfma_f32_16x16x32_bf16 v[40:43], v[140:143], v[208:211], v[40:43]
	v_mfma_f32_16x16x32_bf16 v[40:43], v[148:151], v[212:215], v[40:43]
	s_cmp_eq_u32 s26, 28
	s_cselect_b32 s43, s11, s30
	v_mfma_f32_16x16x32_bf16 v[32:35], v[152:155], v[208:211], v[32:35]
	v_mfma_f32_16x16x32_bf16 v[32:35], v[164:167], v[212:215], v[32:35]
	s_cselect_b32 s42, s18, s27
	s_cselect_b32 s41, s9, s25
	v_mfma_f32_16x16x32_bf16 v[24:27], v[140:143], v[216:219], v[24:27]
	v_mfma_f32_16x16x32_bf16 v[24:27], v[148:151], v[220:223], v[24:27]
	s_cselect_b32 s40, s19, s24
	s_add_i32 s27, 0, 0x14000
	v_mfma_f32_16x16x32_bf16 v[16:19], v[152:155], v[216:219], v[16:19]
	v_mfma_f32_16x16x32_bf16 v[16:19], v[164:167], v[220:223], v[16:19]
	s_setprio 0
	s_setprio 1
	v_mfma_f32_16x16x32_bf16 v[52:55], v[168:171], v[184:187], v[52:55]
	v_mfma_f32_16x16x32_bf16 v[52:55], v[172:175], v[188:191], v[52:55]
	v_mfma_f32_16x16x32_bf16 v[44:47], v[176:179], v[184:187], v[44:47]
	v_mfma_f32_16x16x32_bf16 v[44:47], v[180:183], v[188:191], v[44:47]
	v_mfma_f32_16x16x32_bf16 v[36:39], v[168:171], v[192:195], v[36:39]
	v_mfma_f32_16x16x32_bf16 v[36:39], v[172:175], v[204:207], v[36:39]
	v_mfma_f32_16x16x32_bf16 v[28:31], v[176:179], v[192:195], v[28:31]
	v_mfma_f32_16x16x32_bf16 v[28:31], v[180:183], v[204:207], v[28:31]
	v_mfma_f32_16x16x32_bf16 v[20:23], v[168:171], v[208:211], v[20:23]
	v_mfma_f32_16x16x32_bf16 v[20:23], v[172:175], v[212:215], v[20:23]
	v_mfma_f32_16x16x32_bf16 v[12:15], v[176:179], v[208:211], v[12:15]
	v_mfma_f32_16x16x32_bf16 v[12:15], v[180:183], v[212:215], v[12:15]
	v_mfma_f32_16x16x32_bf16 v[8:11], v[168:171], v[216:219], v[8:11]
	v_mfma_f32_16x16x32_bf16 v[8:11], v[172:175], v[220:223], v[8:11]
	s_setprio 2
	s_barrier
	v_mfma_f32_16x16x32_bf16 v[4:7], v[176:179], v[216:219], v[4:7]
	v_mfma_f32_16x16x32_bf16 v[4:7], v[180:183], v[220:223], v[4:7]
	s_setprio 0
	s_cmp_gt_u32 s26, 29
	s_cbranch_scc0 .LBB0_218

;     __device__ bool next(int i, Unit& u) const { if (i >= 2) return false; const int x = c & 7, j = c >> 3; u.pm = 32 * i + 4 * x + (j & 3); u.pn = j >> 2; return true; }
;     __device__ __forceinline__ void operator()(f32x4 (&acc)[2][2][4][2], const Unit& u, int wr, int wc, int fr_, int fq_, int wid, int lane_) const {
;     ...
;             const int t = wid * 64 + lane, kind = t >> 6, pr = t & 63, bj = kind >> 2, tap = kind & 3;
;             const float* src = (tap < 3) ? (cw + (size_t)tap * FF2 + bj * FF + u.pn * 128 + 2 * pr) : (cb + bj * FF + u.pn * 128 + 2 * pr);
;             const f32x2 wv = *(const f32x2*)src;
; template <class Epi, class Sched, bool ALIGN_EPI = true>
; __device__ __forceinline__ void gemm_phase(LAS unsigned char* lds, const Gemm g, const Sched& S, const Epi& E) {
;     ...
;     const char* cA = (const char*)g.A + ((size_t)cur.pm * BM * g.lda + (size_t)cur.pn * g.a_pn_off) * 2; const char* cB = (const char*)g.Bt + (size_t)cur.pn * BM * g.ldb * 2;
;     PG8_STAGE(PG8_SB(0, 0), cB, voffB); PG8_STAGE(PG8_SB(0, 1), cB + hB, voffB); PG8_STAGE(PG8_SA(0, 0), cA, voffA); PG8_STAGE(PG8_SA(0, 1), cA + hA, voffA);
;     if (wr == 1) PG8_BAR;
;     PG8_WAIT_V(2); PG8_BAR;
;     PG8_STAGE(PG8_SB(1, 0), cB + kstep, voffB); PG8_STAGE(PG8_SA(1, 0), cA + kstep, voffA); PG8_STAGE(PG8_SB(1, 1), cB + hB + kstep, voffB);
;     PG8_WAIT_V(6); PG8_BAR;
;     for (;;) {
;         const bool has_next = S.next(ui + 1, nxt);
;         const char* nA = has_next ? (const char*)g.A + ((size_t)nxt.pm * BM * g.lda + (size_t)nxt.pn * g.a_pn_off) * 2 : cA; const char* nB = has_next ? (const char*)g.Bt + (size_t)nxt.pn * BM * g.ldb * 2 : cB;
;         for (int t = 0; t < nt; t += 2) {
;             const bool last = (t == nt - 2);
;             const char* a1 = cA + (size_t)(t + 1) * kstep;
;             const char* a2 = last ? nA : cA + (size_t)(t + 2) * kstep; const char* b2 = last ? nB : cB + (size_t)(t + 2) * kstep;
;             const char* a3 = a2 + kstep; const char* b3 = b2 + kstep;
;             PG8_LDB(B0, 0, 0); PG8_LDB(B1, 0, 1); PG8_SCHED; PG8_LDA(At, 0, 0); PG8_STAGE(PG8_SA(1, 1), a1 + hA, voffA);
;             PG8_WAIT_V(8); PG8_WAIT_L(0); PG8_BAR; PG8_MMA(0, 0, At, B0); PG8_MMA(0, 1, At, B1); PG8_BAR; PG8_SCHED;
;             PG8_LDA(At, 0, 1); PG8_STAGE(PG8_SB(0, 0), b2, voffB); PG8_STAGE(PG8_SB(0, 1), b2 + hB, voffB); PG8_STAGE(PG8_SA(0, 0), a2, voffA);
.LBB0_827:
	s_ashr_i32 s39, s38, 31
	s_lshl_b64 s[16:17], s[38:39], 20
	s_add_u32 s40, s46, s16
	s_addc_u32 s41, s47, s17
	s_and_b64 s[16:17], s[4:5], exec
	s_cselect_b32 s16, s41, s7
	s_cselect_b32 s17, s40, s6
	s_ashr_i32 s15, s14, 31
	s_lshl_b64 s[18:19], s[14:15], 20
	s_add_u32 s42, s53, s18
	s_addc_u32 s43, s60, s19
	s_and_b64 s[18:19], s[4:5], exec
	s_cselect_b32 s15, s43, s45
	s_cselect_b32 s18, s42, s44
	s_add_u32 s6, s6, 0x80080
	s_addc_u32 s7, s7, 0
	s_add_u32 s19, s44, 0x100
	s_addc_u32 s24, s45, 0
	s_mov_b32 s25, -2
	v_add_u32_e32 v228, s77, v158
	v_ashrrev_i32_e32 v229, 6, v228
	v_and_b32_e32 v230, 3, v229
	v_lshrrev_b32_e32 v231, 8, v228
	v_mul_u32_u24_e32 v228, 0x2c00, v230
	v_lshlrev_b32_e32 v228, 2, v228
	v_mov_b32_e32 v229, 0
	v_lshl_add_u64 v[232:233], s[2:3], 0, v[228:229]
	v_mov_b32_e32 v228, s9
	v_cmp_eq_u32_e32 vcc, 3, v230
	v_mul_i32_i24_e32 v234, 0x1600, v231
	v_ashrrev_i32_e32 v235, 31, v234
	v_cndmask_b32_e32 v233, v233, v228, vcc
	v_mov_b32_e32 v228, s8
	v_cndmask_b32_e32 v232, v232, v228, vcc
	v_lshl_add_u64 v[232:233], v[234:235], 2, v[232:233]
	s_lshl_b32 s26, s82, 7
	s_ashr_i32 s27, s26, 31
	v_lshl_add_u64 v[232:233], s[26:27], 2, v[232:233]
	v_and_b32_e32 v228, 63, v158
	v_lshlrev_b32_e32 v228, 3, v228
	v_mov_b32_e32 v229, 0
	v_lshl_add_u64 v[232:233], v[232:233], 0, v[228:229]
	global_load_dwordx2 v[226:227], v[232:233], off
	s_add_u32 s26, s6, 0xfff80080
	s_addc_u32 s27, s7, -1
	s_add_i32 s30, 0, 0x10000
	s_cmp_eq_u32 s25, 28
	s_cselect_b32 s59, s16, s27
	s_cselect_b32 s58, s17, s26
	v_add_u32_e32 v2, s30, v204
	s_cselect_b32 s45, s15, s24
	s_cselect_b32 s44, s18, s19
	s_add_i32 s31, 0, 0x14000
	ds_read_b128 v[132:135], v2
	ds_read_b128 v[136:139], v2 offset:1024
	ds_read_b128 v[140:143], v2 offset:2048
	ds_read_b128 v[144:147], v2 offset:3072
	v_add_u32_e32 v2, s31, v204
	ds_read_b128 v[148:151], v2
	ds_read_b128 v[152:155], v2 offset:1024
	ds_read_b128 v[174:177], v2 offset:2048
	ds_read_b128 v[178:181], v2 offset:3072
	v_lshl_add_u64 v[156:157], s[6:7], 0, v[170:171]
	s_add_i32 m0, s62, 0xc000
	ds_read_b128 v[182:185], v205
	ds_read_b128 v[186:189], v205 offset:1024
	ds_read_b128 v[190:193], v205 offset:2048
	ds_read_b128 v[194:197], v205 offset:3072
	ds_read_b128 v[206:209], v205 offset:4096
	ds_read_b128 v[210:213], v205 offset:5120
	ds_read_b128 v[214:217], v205 offset:6144
	ds_read_b128 v[218:221], v205 offset:7168
	global_load_lds_dwordx4 v[156:157], off
	v_lshl_add_u64 v[156:157], s[6:7], 0, v[172:173]
	s_add_i32 m0, s62, 0xe000
	s_nop 0
	global_load_lds_dwordx4 v[156:157], off
	s_waitcnt vmcnt(8)
	s_waitcnt lgkmcnt(0)
	s_barrier
	s_setprio 1
	s_waitcnt lgkmcnt(0)
	v_mfma_f32_16x16x32_bf16 v[116:119], v[132:135], v[182:185], 0
	v_mfma_f32_16x16x32_bf16 v[116:119], v[136:139], v[186:189], v[116:119]
	v_mfma_f32_16x16x32_bf16 v[100:103], v[140:143], v[182:185], 0
	v_mfma_f32_16x16x32_bf16 v[100:103], v[144:147], v[186:189], v[100:103]
	v_mfma_f32_16x16x32_bf16 v[108:111], v[132:135], v[190:193], 0
	v_mfma_f32_16x16x32_bf16 v[108:111], v[136:139], v[194:197], v[108:111]
	v_mfma_f32_16x16x32_bf16 v[96:99], v[140:143], v[190:193], 0
	v_mfma_f32_16x16x32_bf16 v[96:99], v[144:147], v[194:197], v[96:99]
	v_mfma_f32_16x16x32_bf16 v[88:91], v[132:135], v[206:209], 0
	v_mfma_f32_16x16x32_bf16 v[88:91], v[136:139], v[210:213], v[88:91]
	v_mfma_f32_16x16x32_bf16 v[84:87], v[140:143], v[206:209], 0
	v_mfma_f32_16x16x32_bf16 v[84:87], v[144:147], v[210:213], v[84:87]
	v_mfma_f32_16x16x32_bf16 v[72:75], v[132:135], v[214:217], 0
	v_mfma_f32_16x16x32_bf16 v[72:75], v[136:139], v[218:221], v[72:75]
	v_mfma_f32_16x16x32_bf16 v[80:83], v[140:143], v[214:217], 0
	v_mfma_f32_16x16x32_bf16 v[80:83], v[144:147], v[218:221], v[80:83]
	s_setprio 0
	s_setprio 1
	v_mfma_f32_16x16x32_bf16 v[128:131], v[148:151], v[182:185], 0
	v_mfma_f32_16x16x32_bf16 v[128:131], v[152:155], v[186:189], v[128:131]
	v_mfma_f32_16x16x32_bf16 v[44:47], v[174:177], v[182:185], 0
	v_mfma_f32_16x16x32_bf16 v[44:47], v[178:181], v[186:189], v[44:47]
	v_mfma_f32_16x16x32_bf16 v[124:127], v[148:151], v[190:193], 0
	v_mfma_f32_16x16x32_bf16 v[124:127], v[152:155], v[194:197], v[124:127]
	v_mfma_f32_16x16x32_bf16 v[36:39], v[174:177], v[190:193], 0
	v_mfma_f32_16x16x32_bf16 v[36:39], v[178:181], v[194:197], v[36:39]
	v_mfma_f32_16x16x32_bf16 v[120:123], v[148:151], v[206:209], 0
	v_mfma_f32_16x16x32_bf16 v[120:123], v[152:155], v[210:213], v[120:123]
	v_mfma_f32_16x16x32_bf16 v[32:35], v[174:177], v[206:209], 0
	v_mfma_f32_16x16x32_bf16 v[32:35], v[178:181], v[210:213], v[32:35]
	v_mfma_f32_16x16x32_bf16 v[112:115], v[148:151], v[214:217], 0
	v_mfma_f32_16x16x32_bf16 v[112:115], v[152:155], v[218:221], v[112:115]
	s_setprio 2
	s_barrier
	v_mfma_f32_16x16x32_bf16 v[28:31], v[174:177], v[214:217], 0
	v_mfma_f32_16x16x32_bf16 v[28:31], v[178:181], v[218:221], v[28:31]
	s_setprio 0
	s_add_i32 s26, s30, s61
	v_lshl_add_u64 v[156:157], s[44:45], 0, v[166:167]
	s_mov_b32 m0, s26
	ds_read_b128 v[182:185], v205 offset:16384
	ds_read_b128 v[186:189], v205 offset:17408
	ds_read_b128 v[190:193], v205 offset:18432
	ds_read_b128 v[194:197], v205 offset:19456
	ds_read_b128 v[206:209], v205 offset:20480
	ds_read_b128 v[210:213], v205 offset:21504
	ds_read_b128 v[214:217], v205 offset:22528
	ds_read_b128 v[218:221], v205 offset:23552
	global_load_lds_dwordx4 v[156:157], off
	s_add_i32 m0, s26, 0x2000
	s_add_u32 s26, s44, 0x80000
	v_lshl_add_u64 v[160:161], s[44:45], 0, v[0:1]
	s_addc_u32 s27, s45, 0
	s_add_i32 s30, s31, s61
	global_load_lds_dwordx4 v[160:161], off
	v_lshl_add_u64 v[162:163], s[26:27], 0, v[166:167]
	s_mov_b32 m0, s30
	v_lshl_add_u64 v[222:223], s[58:59], 0, v[164:165]
	global_load_lds_dwordx4 v[162:163], off
	v_lshl_add_u64 v[162:163], s[26:27], 0, v[0:1]
	s_add_i32 m0, s30, 0x2000
	s_nop 0
	global_load_lds_dwordx4 v[162:163], off
	v_lshl_add_u64 v[162:163], s[58:59], 0, v[168:169]
	s_mov_b32 m0, s62
	s_nop 0
	global_load_lds_dwordx4 v[162:163], off
	s_mov_b32 m0, s63
	s_nop 0
	global_load_lds_dwordx4 v[222:223], off
	s_waitcnt vmcnt(8)
	s_waitcnt lgkmcnt(0)
	s_barrier
; #define PG8_STAGE(bufoff, gbase, voff) do { _Pragma("unroll") for (int _i = 0; _i < 2; ++_i) \
;         __builtin_amdgcn_global_load_lds((const unsigned*)((const char*)(gbase) + (voff)[_i]), (LAS unsigned*)(lds + (bufoff) + ldsw + _i * 8192), 16, 0, 0); } while (0)
; #define PG8_LDA(dst, b, h) do { _Pragma("unroll") for (int m = 0; m < 4; ++m) _Pragma("unroll") for (int k = 0; k < 2; ++k) dst[m][k] = *(const LAS bf16x8*)(lds + PG8_SA(b, h) + aoff + m * 2048 + k * 1024); } while (0)
; #define PG8_LDB(dst, b, h) do { _Pragma("unroll") for (int n = 0; n < 2; ++n) _Pragma("unroll") for (int k = 0; k < 2; ++k) dst[n][k] = *(const LAS bf16x8*)(lds + PG8_SB(b, h) + boff + n * 2048 + k * 1024); } while (0)
; #define PG8_MMA(ai, bj, At, Bt) do { __builtin_amdgcn_s_setprio(1); _Pragma("unroll") for (int m = 0; m < 4; ++m) _Pragma("unroll") for (int n = 0; n < 2; ++n) _Pragma("unroll") for (int k = 0; k < 2; ++k) \
;         acc[ai][bj][m][n] = __builtin_amdgcn_mfma_f32_16x16x32_bf16(Bt[n][k], At[m][k], acc[ai][bj][m][n], 0, 0, 0); __builtin_amdgcn_s_setprio(0); } while (0)
; #define PG8_WAIT_V(n) asm volatile("s_waitcnt vmcnt(" #n ")" ::: "memory")
; #define PG8_WAIT_L(n) asm volatile("s_waitcnt lgkmcnt(" #n ")" ::: "memory")
; #define PG8_BAR __builtin_amdgcn_s_barrier()
; #define PG8_SCHED __builtin_amdgcn_sched_barrier(0)
; template <class Epi, class Sched, bool ALIGN_EPI = true>
; __device__ __forceinline__ void gemm_phase(LAS unsigned char* lds, const Gemm g, const Sched& S, const Epi& E) {
;     ...
;             PG8_WAIT_V(8); PG8_WAIT_L(0); PG8_BAR; PG8_MMA(1, 0, At, B0); PG8_MMA(1, 1, At, B1); PG8_BAR; PG8_SCHED;
;             PG8_LDB(B0, 1, 0); PG8_LDB(B1, 1, 1); PG8_SCHED; PG8_LDA(At, 1, 0); PG8_STAGE(PG8_SA(0, 1), a2 + hA, voffA);
;             PG8_WAIT_V(8); PG8_WAIT_L(0); PG8_BAR; PG8_MMA(0, 0, At, B0); PG8_MMA(0, 1, At, B1); PG8_BAR; PG8_SCHED;
	s_setprio 1
	s_waitcnt lgkmcnt(0)
	v_mfma_f32_16x16x32_bf16 v[60:63], v[132:135], v[182:185], 0
	v_mfma_f32_16x16x32_bf16 v[60:63], v[136:139], v[186:189], v[60:63]
	v_mfma_f32_16x16x32_bf16 v[68:71], v[140:143], v[182:185], 0
	v_mfma_f32_16x16x32_bf16 v[68:71], v[144:147], v[186:189], v[68:71]
	v_mfma_f32_16x16x32_bf16 v[40:43], v[132:135], v[190:193], 0
	v_mfma_f32_16x16x32_bf16 v[40:43], v[136:139], v[194:197], v[40:43]
	v_mfma_f32_16x16x32_bf16 v[64:67], v[140:143], v[190:193], 0
	v_mfma_f32_16x16x32_bf16 v[64:67], v[144:147], v[194:197], v[64:67]
	v_mfma_f32_16x16x32_bf16 v[24:27], v[132:135], v[206:209], 0
	v_mfma_f32_16x16x32_bf16 v[24:27], v[136:139], v[210:213], v[24:27]
	v_mfma_f32_16x16x32_bf16 v[56:59], v[140:143], v[206:209], 0
	v_mfma_f32_16x16x32_bf16 v[56:59], v[144:147], v[210:213], v[56:59]
	v_mfma_f32_16x16x32_bf16 v[12:15], v[132:135], v[214:217], 0
	v_mfma_f32_16x16x32_bf16 v[12:15], v[136:139], v[218:221], v[12:15]
	v_mfma_f32_16x16x32_bf16 v[48:51], v[140:143], v[214:217], 0
	v_mfma_f32_16x16x32_bf16 v[48:51], v[144:147], v[218:221], v[48:51]
	s_setprio 0
	s_setprio 1
	v_mfma_f32_16x16x32_bf16 v[104:107], v[148:151], v[182:185], 0
	v_mfma_f32_16x16x32_bf16 v[104:107], v[152:155], v[186:189], v[104:107]
	v_mfma_f32_16x16x32_bf16 v[20:23], v[174:177], v[182:185], 0
	v_mfma_f32_16x16x32_bf16 v[20:23], v[178:181], v[186:189], v[20:23]
	v_mfma_f32_16x16x32_bf16 v[92:95], v[148:151], v[190:193], 0
	v_mfma_f32_16x16x32_bf16 v[92:95], v[152:155], v[194:197], v[92:95]
	v_mfma_f32_16x16x32_bf16 v[16:19], v[174:177], v[190:193], 0
	v_mfma_f32_16x16x32_bf16 v[16:19], v[178:181], v[194:197], v[16:19]
	v_mfma_f32_16x16x32_bf16 v[76:79], v[148:151], v[206:209], 0
	v_mfma_f32_16x16x32_bf16 v[76:79], v[152:155], v[210:213], v[76:79]
	v_mfma_f32_16x16x32_bf16 v[8:11], v[174:177], v[206:209], 0
	v_mfma_f32_16x16x32_bf16 v[8:11], v[178:181], v[210:213], v[8:11]
	v_mfma_f32_16x16x32_bf16 v[52:55], v[148:151], v[214:217], 0
	v_mfma_f32_16x16x32_bf16 v[52:55], v[152:155], v[218:221], v[52:55]
	s_setprio 2
	s_barrier
	v_mfma_f32_16x16x32_bf16 v[4:7], v[174:177], v[214:217], 0
	v_mfma_f32_16x16x32_bf16 v[4:7], v[178:181], v[218:221], v[4:7]
	s_setprio 0
	s_add_i32 s30, 0, 0x18000
	v_add_u32_e32 v2, s30, v204
	s_add_i32 s31, 0, 0x1c000
	ds_read_b128 v[132:135], v2
	ds_read_b128 v[136:139], v2 offset:1024
	ds_read_b128 v[140:143], v2 offset:2048
	ds_read_b128 v[144:147], v2 offset:3072
	v_add_u32_e32 v2, s31, v204
	ds_read_b128 v[148:151], v2
	ds_read_b128 v[152:155], v2 offset:1024
	ds_read_b128 v[174:177], v2 offset:2048
	ds_read_b128 v[178:181], v2 offset:3072
	s_add_u32 s26, s58, 0x80000
	s_addc_u32 s27, s59, 0
	s_mov_b32 m0, s64
	v_lshl_add_u64 v[224:225], s[26:27], 0, v[168:169]
	ds_read_b128 v[182:185], v205 offset:32768
	ds_read_b128 v[186:189], v205 offset:33792
	ds_read_b128 v[190:193], v205 offset:34816
	ds_read_b128 v[194:197], v205 offset:35840
	ds_read_b128 v[206:209], v205 offset:36864
	ds_read_b128 v[210:213], v205 offset:37888
	ds_read_b128 v[214:217], v205 offset:38912
	ds_read_b128 v[218:221], v205 offset:39936
	global_load_lds_dwordx4 v[224:225], off
	v_lshl_add_u64 v[224:225], s[26:27], 0, v[164:165]
	s_mov_b32 m0, s65
	s_nop 0
	global_load_lds_dwordx4 v[224:225], off
	s_waitcnt vmcnt(8)
	s_waitcnt lgkmcnt(0)
	s_barrier
	s_setprio 1
	s_waitcnt lgkmcnt(0)
	v_mfma_f32_16x16x32_bf16 v[116:119], v[132:135], v[182:185], v[116:119]
	v_mfma_f32_16x16x32_bf16 v[116:119], v[136:139], v[186:189], v[116:119]
	v_mfma_f32_16x16x32_bf16 v[100:103], v[140:143], v[182:185], v[100:103]
	v_mfma_f32_16x16x32_bf16 v[100:103], v[144:147], v[186:189], v[100:103]
	v_mfma_f32_16x16x32_bf16 v[108:111], v[132:135], v[190:193], v[108:111]
	v_mfma_f32_16x16x32_bf16 v[108:111], v[136:139], v[194:197], v[108:111]
	v_mfma_f32_16x16x32_bf16 v[96:99], v[140:143], v[190:193], v[96:99]
	v_mfma_f32_16x16x32_bf16 v[96:99], v[144:147], v[194:197], v[96:99]
	v_mfma_f32_16x16x32_bf16 v[88:91], v[132:135], v[206:209], v[88:91]
	v_mfma_f32_16x16x32_bf16 v[88:91], v[136:139], v[210:213], v[88:91]
	v_mfma_f32_16x16x32_bf16 v[84:87], v[140:143], v[206:209], v[84:87]
	v_mfma_f32_16x16x32_bf16 v[84:87], v[144:147], v[210:213], v[84:87]
	v_mfma_f32_16x16x32_bf16 v[72:75], v[132:135], v[214:217], v[72:75]
	v_mfma_f32_16x16x32_bf16 v[72:75], v[136:139], v[218:221], v[72:75]
	v_mfma_f32_16x16x32_bf16 v[80:83], v[140:143], v[214:217], v[80:83]
	v_mfma_f32_16x16x32_bf16 v[80:83], v[144:147], v[218:221], v[80:83]
	s_setprio 0
	s_setprio 1
	v_mfma_f32_16x16x32_bf16 v[128:131], v[148:151], v[182:185], v[128:131]
	v_mfma_f32_16x16x32_bf16 v[128:131], v[152:155], v[186:189], v[128:131]
	v_mfma_f32_16x16x32_bf16 v[44:47], v[174:177], v[182:185], v[44:47]
	v_mfma_f32_16x16x32_bf16 v[44:47], v[178:181], v[186:189], v[44:47]
	v_mfma_f32_16x16x32_bf16 v[124:127], v[148:151], v[190:193], v[124:127]
	v_mfma_f32_16x16x32_bf16 v[124:127], v[152:155], v[194:197], v[124:127]
	v_mfma_f32_16x16x32_bf16 v[36:39], v[174:177], v[190:193], v[36:39]
	v_mfma_f32_16x16x32_bf16 v[36:39], v[178:181], v[194:197], v[36:39]
	v_mfma_f32_16x16x32_bf16 v[120:123], v[148:151], v[206:209], v[120:123]
	v_mfma_f32_16x16x32_bf16 v[120:123], v[152:155], v[210:213], v[120:123]
	v_mfma_f32_16x16x32_bf16 v[32:35], v[174:177], v[206:209], v[32:35]
	v_mfma_f32_16x16x32_bf16 v[32:35], v[178:181], v[210:213], v[32:35]
	v_mfma_f32_16x16x32_bf16 v[112:115], v[148:151], v[214:217], v[112:115]
	v_mfma_f32_16x16x32_bf16 v[112:115], v[152:155], v[218:221], v[112:115]
	s_setprio 2
	s_barrier
; #define PG8_STAGE(bufoff, gbase, voff) do { _Pragma("unroll") for (int _i = 0; _i < 2; ++_i) \
;         __builtin_amdgcn_global_load_lds((const unsigned*)((const char*)(gbase) + (voff)[_i]), (LAS unsigned*)(lds + (bufoff) + ldsw + _i * 8192), 16, 0, 0); } while (0)
; #define PG8_LDA(dst, b, h) do { _Pragma("unroll") for (int m = 0; m < 4; ++m) _Pragma("unroll") for (int k = 0; k < 2; ++k) dst[m][k] = *(const LAS bf16x8*)(lds + PG8_SA(b, h) + aoff + m * 2048 + k * 1024); } while (0)
; #define PG8_LDB(dst, b, h) do { _Pragma("unroll") for (int n = 0; n < 2; ++n) _Pragma("unroll") for (int k = 0; k < 2; ++k) dst[n][k] = *(const LAS bf16x8*)(lds + PG8_SB(b, h) + boff + n * 2048 + k * 1024); } while (0)
; #define PG8_MMA(ai, bj, At, Bt) do { __builtin_amdgcn_s_setprio(1); _Pragma("unroll") for (int m = 0; m < 4; ++m) _Pragma("unroll") for (int n = 0; n < 2; ++n) _Pragma("unroll") for (int k = 0; k < 2; ++k) \
;         acc[ai][bj][m][n] = __builtin_amdgcn_mfma_f32_16x16x32_bf16(Bt[n][k], At[m][k], acc[ai][bj][m][n], 0, 0, 0); __builtin_amdgcn_s_setprio(0); } while (0)
; #define PG8_WAIT_V(n) asm volatile("s_waitcnt vmcnt(" #n ")" ::: "memory")
; #define PG8_WAIT_L(n) asm volatile("s_waitcnt lgkmcnt(" #n ")" ::: "memory")
; #define PG8_BAR __builtin_amdgcn_s_barrier()
; #define PG8_SCHED __builtin_amdgcn_sched_barrier(0)
; template <class Epi, class Sched, bool ALIGN_EPI = true>
; __device__ __forceinline__ void gemm_phase(LAS unsigned char* lds, const Gemm g, const Sched& S, const Epi& E) {
;     ...
;             const bool last = (t == nt - 2);
;             const char* a1 = cA + (size_t)(t + 1) * kstep;
;             const char* a2 = last ? nA : cA + (size_t)(t + 2) * kstep; const char* b2 = last ? nB : cB + (size_t)(t + 2) * kstep;
;             const char* a3 = a2 + kstep; const char* b3 = b2 + kstep;
;             PG8_LDB(B0, 0, 0); PG8_LDB(B1, 0, 1); PG8_SCHED; PG8_LDA(At, 0, 0); PG8_STAGE(PG8_SA(1, 1), a1 + hA, voffA);
;     ...
;             PG8_WAIT_V(8); PG8_WAIT_L(0); PG8_BAR; PG8_MMA(0, 0, At, B0); PG8_MMA(0, 1, At, B1); PG8_BAR; PG8_SCHED;
;             PG8_LDA(At, 1, 1); PG8_STAGE(PG8_SB(1, 0), b3, voffB); PG8_STAGE(PG8_SB(1, 1), b3 + hB, voffB); PG8_STAGE(PG8_SA(1, 0), a3, voffA);
;             PG8_WAIT_V(8); PG8_WAIT_L(0); PG8_BAR; PG8_MMA(1, 0, At, B0); PG8_MMA(1, 1, At, B1); PG8_BAR; PG8_SCHED;
	v_mfma_f32_16x16x32_bf16 v[28:31], v[174:177], v[214:217], v[28:31]
	v_mfma_f32_16x16x32_bf16 v[28:31], v[178:181], v[218:221], v[28:31]
	s_setprio 0
	s_add_i32 s26, s30, s61
	v_lshl_add_u64 v[156:157], v[156:157], 0, s[86:87]
	s_mov_b32 m0, s26
	ds_read_b128 v[182:185], v205 offset:49152
	ds_read_b128 v[186:189], v205 offset:50176
	ds_read_b128 v[190:193], v205 offset:51200
	ds_read_b128 v[194:197], v205 offset:52224
	ds_read_b128 v[206:209], v205 offset:53248
	ds_read_b128 v[210:213], v205 offset:54272
	ds_read_b128 v[214:217], v205 offset:55296
	ds_read_b128 v[218:221], v205 offset:56320
	global_load_lds_dwordx4 v[156:157], off
	s_add_i32 m0, s26, 0x2000
	s_add_u32 s26, s44, 0x80080
	v_lshl_add_u64 v[156:157], v[160:161], 0, s[86:87]
	s_addc_u32 s27, s45, 0
	s_add_i32 s30, s31, s61
	global_load_lds_dwordx4 v[156:157], off
	v_lshl_add_u64 v[156:157], s[26:27], 0, v[166:167]
	s_mov_b32 m0, s30
	s_nop 0
	global_load_lds_dwordx4 v[156:157], off
	v_lshl_add_u64 v[156:157], s[26:27], 0, v[0:1]
	s_add_i32 m0, s30, 0x2000
	s_nop 0
	global_load_lds_dwordx4 v[156:157], off
	v_lshl_add_u64 v[156:157], v[162:163], 0, s[86:87]
	s_mov_b32 m0, s75
	s_nop 0
	global_load_lds_dwordx4 v[156:157], off
	v_lshl_add_u64 v[156:157], v[222:223], 0, s[86:87]
	s_mov_b32 m0, s76
	s_nop 0
	global_load_lds_dwordx4 v[156:157], off
	s_waitcnt vmcnt(8)
	s_waitcnt lgkmcnt(0)
	s_barrier
	s_setprio 1
	s_waitcnt lgkmcnt(0)
	v_mfma_f32_16x16x32_bf16 v[60:63], v[132:135], v[182:185], v[60:63]
	v_mfma_f32_16x16x32_bf16 v[60:63], v[136:139], v[186:189], v[60:63]
	s_add_i32 s25, s25, 2
	s_add_u32 s6, s6, 0x100
	v_mfma_f32_16x16x32_bf16 v[68:71], v[140:143], v[182:185], v[68:71]
	v_mfma_f32_16x16x32_bf16 v[68:71], v[144:147], v[186:189], v[68:71]
	s_addc_u32 s7, s7, 0
	s_add_u32 s19, s19, 0x100
	v_mfma_f32_16x16x32_bf16 v[40:43], v[132:135], v[190:193], v[40:43]
	v_mfma_f32_16x16x32_bf16 v[40:43], v[136:139], v[194:197], v[40:43]
	s_addc_u32 s24, s24, 0
	s_add_u32 s26, s6, 0xfff80080
	v_mfma_f32_16x16x32_bf16 v[64:67], v[140:143], v[190:193], v[64:67]
	v_mfma_f32_16x16x32_bf16 v[64:67], v[144:147], v[194:197], v[64:67]
	s_addc_u32 s27, s7, -1
	s_add_i32 s30, 0, 0x10000
	v_mfma_f32_16x16x32_bf16 v[24:27], v[132:135], v[206:209], v[24:27]
	v_mfma_f32_16x16x32_bf16 v[24:27], v[136:139], v[210:213], v[24:27]
	s_cmp_eq_u32 s25, 28
	s_cselect_b32 s59, s16, s27
	v_mfma_f32_16x16x32_bf16 v[56:59], v[140:143], v[206:209], v[56:59]
	v_mfma_f32_16x16x32_bf16 v[56:59], v[144:147], v[210:213], v[56:59]
	s_cselect_b32 s58, s17, s26
	s_cselect_b32 s45, s15, s24
	v_mfma_f32_16x16x32_bf16 v[12:15], v[132:135], v[214:217], v[12:15]
	v_mfma_f32_16x16x32_bf16 v[12:15], v[136:139], v[218:221], v[12:15]
	s_cselect_b32 s44, s18, s19
	s_add_i32 s31, 0, 0x14000
	v_mfma_f32_16x16x32_bf16 v[48:51], v[140:143], v[214:217], v[48:51]
	v_mfma_f32_16x16x32_bf16 v[48:51], v[144:147], v[218:221], v[48:51]
	s_setprio 0
	s_setprio 1
	v_mfma_f32_16x16x32_bf16 v[104:107], v[148:151], v[182:185], v[104:107]
	v_mfma_f32_16x16x32_bf16 v[104:107], v[152:155], v[186:189], v[104:107]
	v_mfma_f32_16x16x32_bf16 v[20:23], v[174:177], v[182:185], v[20:23]
	v_mfma_f32_16x16x32_bf16 v[20:23], v[178:181], v[186:189], v[20:23]
	v_mfma_f32_16x16x32_bf16 v[92:95], v[148:151], v[190:193], v[92:95]
	v_mfma_f32_16x16x32_bf16 v[92:95], v[152:155], v[194:197], v[92:95]
	v_mfma_f32_16x16x32_bf16 v[16:19], v[174:177], v[190:193], v[16:19]
	v_mfma_f32_16x16x32_bf16 v[16:19], v[178:181], v[194:197], v[16:19]
	v_mfma_f32_16x16x32_bf16 v[76:79], v[148:151], v[206:209], v[76:79]
	v_mfma_f32_16x16x32_bf16 v[76:79], v[152:155], v[210:213], v[76:79]
	v_mfma_f32_16x16x32_bf16 v[8:11], v[174:177], v[206:209], v[8:11]
	v_mfma_f32_16x16x32_bf16 v[8:11], v[178:181], v[210:213], v[8:11]
	v_mfma_f32_16x16x32_bf16 v[52:55], v[148:151], v[214:217], v[52:55]
	v_mfma_f32_16x16x32_bf16 v[52:55], v[152:155], v[218:221], v[52:55]
	s_setprio 2
	s_barrier
	v_mfma_f32_16x16x32_bf16 v[4:7], v[174:177], v[214:217], v[4:7]
	v_mfma_f32_16x16x32_bf16 v[4:7], v[178:181], v[218:221], v[4:7]
	s_setprio 0
	s_cmp_gt_u32 s25, 29
	s_cbranch_scc1 .Lpeel_exit_828
.LBB0_828:
	v_add_u32_e32 v2, s30, v204
	ds_read_b128 v[132:135], v2
	ds_read_b128 v[136:139], v2 offset:1024
	ds_read_b128 v[140:143], v2 offset:2048
	ds_read_b128 v[144:147], v2 offset:3072
	v_add_u32_e32 v2, s31, v204
	ds_read_b128 v[148:151], v2
	ds_read_b128 v[152:155], v2 offset:1024
	ds_read_b128 v[174:177], v2 offset:2048
	ds_read_b128 v[178:181], v2 offset:3072
	v_lshl_add_u64 v[156:157], s[6:7], 0, v[170:171]
	s_add_i32 m0, s62, 0xc000
	ds_read_b128 v[182:185], v205
	ds_read_b128 v[186:189], v205 offset:1024
	ds_read_b128 v[190:193], v205 offset:2048
	ds_read_b128 v[194:197], v205 offset:3072
	ds_read_b128 v[206:209], v205 offset:4096
	ds_read_b128 v[210:213], v205 offset:5120
	ds_read_b128 v[214:217], v205 offset:6144
	ds_read_b128 v[218:221], v205 offset:7168
	global_load_lds_dwordx4 v[156:157], off
	v_lshl_add_u64 v[156:157], s[6:7], 0, v[172:173]
	s_add_i32 m0, s62, 0xe000
	s_nop 0
	global_load_lds_dwordx4 v[156:157], off
	s_waitcnt vmcnt(8)
	s_waitcnt lgkmcnt(0)
	s_barrier
; #define PG8_STAGE(bufoff, gbase, voff) do { _Pragma("unroll") for (int _i = 0; _i < 2; ++_i) \
;         __builtin_amdgcn_global_load_lds((const unsigned*)((const char*)(gbase) + (voff)[_i]), (LAS unsigned*)(lds + (bufoff) + ldsw + _i * 8192), 16, 0, 0); } while (0)
; #define PG8_LDA(dst, b, h) do { _Pragma("unroll") for (int m = 0; m < 4; ++m) _Pragma("unroll") for (int k = 0; k < 2; ++k) dst[m][k] = *(const LAS bf16x8*)(lds + PG8_SA(b, h) + aoff + m * 2048 + k * 1024); } while (0)
; #define PG8_MMA(ai, bj, At, Bt) do { __builtin_amdgcn_s_setprio(1); _Pragma("unroll") for (int m = 0; m < 4; ++m) _Pragma("unroll") for (int n = 0; n < 2; ++n) _Pragma("unroll") for (int k = 0; k < 2; ++k) \
;         acc[ai][bj][m][n] = __builtin_amdgcn_mfma_f32_16x16x32_bf16(Bt[n][k], At[m][k], acc[ai][bj][m][n], 0, 0, 0); __builtin_amdgcn_s_setprio(0); } while (0)
; #define PG8_WAIT_V(n) asm volatile("s_waitcnt vmcnt(" #n ")" ::: "memory")
; #define PG8_WAIT_L(n) asm volatile("s_waitcnt lgkmcnt(" #n ")" ::: "memory")
; #define PG8_BAR __builtin_amdgcn_s_barrier()
; #define PG8_SCHED __builtin_amdgcn_sched_barrier(0)
; template <class Epi, class Sched, bool ALIGN_EPI = true>
; __device__ __forceinline__ void gemm_phase(LAS unsigned char* lds, const Gemm g, const Sched& S, const Epi& E) {
;     ...
;             PG8_WAIT_V(8); PG8_WAIT_L(0); PG8_BAR; PG8_MMA(0, 0, At, B0); PG8_MMA(0, 1, At, B1); PG8_BAR; PG8_SCHED;
;             PG8_LDA(At, 0, 1); PG8_STAGE(PG8_SB(0, 0), b2, voffB); PG8_STAGE(PG8_SB(0, 1), b2 + hB, voffB); PG8_STAGE(PG8_SA(0, 0), a2, voffA);
;             PG8_WAIT_V(8); PG8_WAIT_L(0); PG8_BAR; PG8_MMA(1, 0, At, B0); PG8_MMA(1, 1, At, B1); PG8_BAR; PG8_SCHED;
	s_setprio 1
	s_waitcnt lgkmcnt(0)
	v_mfma_f32_16x16x32_bf16 v[116:119], v[132:135], v[182:185], v[116:119]
	v_mfma_f32_16x16x32_bf16 v[116:119], v[136:139], v[186:189], v[116:119]
	v_mfma_f32_16x16x32_bf16 v[100:103], v[140:143], v[182:185], v[100:103]
	v_mfma_f32_16x16x32_bf16 v[100:103], v[144:147], v[186:189], v[100:103]
	v_mfma_f32_16x16x32_bf16 v[108:111], v[132:135], v[190:193], v[108:111]
	v_mfma_f32_16x16x32_bf16 v[108:111], v[136:139], v[194:197], v[108:111]
	v_mfma_f32_16x16x32_bf16 v[96:99], v[140:143], v[190:193], v[96:99]
	v_mfma_f32_16x16x32_bf16 v[96:99], v[144:147], v[194:197], v[96:99]
	v_mfma_f32_16x16x32_bf16 v[88:91], v[132:135], v[206:209], v[88:91]
	v_mfma_f32_16x16x32_bf16 v[88:91], v[136:139], v[210:213], v[88:91]
	v_mfma_f32_16x16x32_bf16 v[84:87], v[140:143], v[206:209], v[84:87]
	v_mfma_f32_16x16x32_bf16 v[84:87], v[144:147], v[210:213], v[84:87]
	v_mfma_f32_16x16x32_bf16 v[72:75], v[132:135], v[214:217], v[72:75]
	v_mfma_f32_16x16x32_bf16 v[72:75], v[136:139], v[218:221], v[72:75]
	v_mfma_f32_16x16x32_bf16 v[80:83], v[140:143], v[214:217], v[80:83]
	v_mfma_f32_16x16x32_bf16 v[80:83], v[144:147], v[218:221], v[80:83]
	s_setprio 0
	s_setprio 1
	v_mfma_f32_16x16x32_bf16 v[128:131], v[148:151], v[182:185], v[128:131]
	v_mfma_f32_16x16x32_bf16 v[128:131], v[152:155], v[186:189], v[128:131]
	v_mfma_f32_16x16x32_bf16 v[44:47], v[174:177], v[182:185], v[44:47]
	v_mfma_f32_16x16x32_bf16 v[44:47], v[178:181], v[186:189], v[44:47]
	v_mfma_f32_16x16x32_bf16 v[124:127], v[148:151], v[190:193], v[124:127]
	v_mfma_f32_16x16x32_bf16 v[124:127], v[152:155], v[194:197], v[124:127]
	v_mfma_f32_16x16x32_bf16 v[36:39], v[174:177], v[190:193], v[36:39]
	v_mfma_f32_16x16x32_bf16 v[36:39], v[178:181], v[194:197], v[36:39]
	v_mfma_f32_16x16x32_bf16 v[120:123], v[148:151], v[206:209], v[120:123]
	v_mfma_f32_16x16x32_bf16 v[120:123], v[152:155], v[210:213], v[120:123]
	v_mfma_f32_16x16x32_bf16 v[32:35], v[174:177], v[206:209], v[32:35]
	v_mfma_f32_16x16x32_bf16 v[32:35], v[178:181], v[210:213], v[32:35]
	v_mfma_f32_16x16x32_bf16 v[112:115], v[148:151], v[214:217], v[112:115]
	v_mfma_f32_16x16x32_bf16 v[112:115], v[152:155], v[218:221], v[112:115]
	s_setprio 2
	s_barrier
	v_mfma_f32_16x16x32_bf16 v[28:31], v[174:177], v[214:217], v[28:31]
	v_mfma_f32_16x16x32_bf16 v[28:31], v[178:181], v[218:221], v[28:31]
	s_setprio 0
	s_add_i32 s26, s30, s61
	v_lshl_add_u64 v[156:157], s[44:45], 0, v[166:167]
	s_mov_b32 m0, s26
	ds_read_b128 v[182:185], v205 offset:16384
	ds_read_b128 v[186:189], v205 offset:17408
	ds_read_b128 v[190:193], v205 offset:18432
	ds_read_b128 v[194:197], v205 offset:19456
	ds_read_b128 v[206:209], v205 offset:20480
	ds_read_b128 v[210:213], v205 offset:21504
	ds_read_b128 v[214:217], v205 offset:22528
	ds_read_b128 v[218:221], v205 offset:23552
	global_load_lds_dwordx4 v[156:157], off
	s_add_i32 m0, s26, 0x2000
	s_add_u32 s26, s44, 0x80000
	v_lshl_add_u64 v[160:161], s[44:45], 0, v[0:1]
	s_addc_u32 s27, s45, 0
	s_add_i32 s30, s31, s61
	global_load_lds_dwordx4 v[160:161], off
	v_lshl_add_u64 v[162:163], s[26:27], 0, v[166:167]
	s_mov_b32 m0, s30
	v_lshl_add_u64 v[222:223], s[58:59], 0, v[164:165]
	global_load_lds_dwordx4 v[162:163], off
	v_lshl_add_u64 v[162:163], s[26:27], 0, v[0:1]
	s_add_i32 m0, s30, 0x2000
	s_nop 0
	global_load_lds_dwordx4 v[162:163], off
	v_lshl_add_u64 v[162:163], s[58:59], 0, v[168:169]
	s_mov_b32 m0, s62
	s_nop 0
	global_load_lds_dwordx4 v[162:163], off
	s_mov_b32 m0, s63
	s_nop 0
	global_load_lds_dwordx4 v[222:223], off
	s_waitcnt vmcnt(8)
	s_waitcnt lgkmcnt(0)
	s_barrier
	s_setprio 1
	s_waitcnt lgkmcnt(0)
	v_mfma_f32_16x16x32_bf16 v[60:63], v[132:135], v[182:185], v[60:63]
	v_mfma_f32_16x16x32_bf16 v[60:63], v[136:139], v[186:189], v[60:63]
	v_mfma_f32_16x16x32_bf16 v[68:71], v[140:143], v[182:185], v[68:71]
	v_mfma_f32_16x16x32_bf16 v[68:71], v[144:147], v[186:189], v[68:71]
	v_mfma_f32_16x16x32_bf16 v[40:43], v[132:135], v[190:193], v[40:43]
	v_mfma_f32_16x16x32_bf16 v[40:43], v[136:139], v[194:197], v[40:43]
	v_mfma_f32_16x16x32_bf16 v[64:67], v[140:143], v[190:193], v[64:67]
	v_mfma_f32_16x16x32_bf16 v[64:67], v[144:147], v[194:197], v[64:67]
	v_mfma_f32_16x16x32_bf16 v[24:27], v[132:135], v[206:209], v[24:27]
	v_mfma_f32_16x16x32_bf16 v[24:27], v[136:139], v[210:213], v[24:27]
	v_mfma_f32_16x16x32_bf16 v[56:59], v[140:143], v[206:209], v[56:59]
	v_mfma_f32_16x16x32_bf16 v[56:59], v[144:147], v[210:213], v[56:59]
	v_mfma_f32_16x16x32_bf16 v[12:15], v[132:135], v[214:217], v[12:15]
	v_mfma_f32_16x16x32_bf16 v[12:15], v[136:139], v[218:221], v[12:15]
	v_mfma_f32_16x16x32_bf16 v[48:51], v[140:143], v[214:217], v[48:51]
	v_mfma_f32_16x16x32_bf16 v[48:51], v[144:147], v[218:221], v[48:51]
	s_setprio 0
	s_setprio 1
	v_mfma_f32_16x16x32_bf16 v[104:107], v[148:151], v[182:185], v[104:107]
	v_mfma_f32_16x16x32_bf16 v[104:107], v[152:155], v[186:189], v[104:107]
	v_mfma_f32_16x16x32_bf16 v[20:23], v[174:177], v[182:185], v[20:23]
	v_mfma_f32_16x16x32_bf16 v[20:23], v[178:181], v[186:189], v[20:23]
	v_mfma_f32_16x16x32_bf16 v[92:95], v[148:151], v[190:193], v[92:95]
	v_mfma_f32_16x16x32_bf16 v[92:95], v[152:155], v[194:197], v[92:95]
	v_mfma_f32_16x16x32_bf16 v[16:19], v[174:177], v[190:193], v[16:19]
	v_mfma_f32_16x16x32_bf16 v[16:19], v[178:181], v[194:197], v[16:19]
	v_mfma_f32_16x16x32_bf16 v[76:79], v[148:151], v[206:209], v[76:79]
	v_mfma_f32_16x16x32_bf16 v[76:79], v[152:155], v[210:213], v[76:79]
	v_mfma_f32_16x16x32_bf16 v[8:11], v[174:177], v[206:209], v[8:11]
	v_mfma_f32_16x16x32_bf16 v[8:11], v[178:181], v[210:213], v[8:11]
	v_mfma_f32_16x16x32_bf16 v[52:55], v[148:151], v[214:217], v[52:55]
	v_mfma_f32_16x16x32_bf16 v[52:55], v[152:155], v[218:221], v[52:55]
	s_setprio 2
	s_barrier
; #define PG8_STAGE(bufoff, gbase, voff) do { _Pragma("unroll") for (int _i = 0; _i < 2; ++_i) \
;         __builtin_amdgcn_global_load_lds((const unsigned*)((const char*)(gbase) + (voff)[_i]), (LAS unsigned*)(lds + (bufoff) + ldsw + _i * 8192), 16, 0, 0); } while (0)
; #define PG8_LDA(dst, b, h) do { _Pragma("unroll") for (int m = 0; m < 4; ++m) _Pragma("unroll") for (int k = 0; k < 2; ++k) dst[m][k] = *(const LAS bf16x8*)(lds + PG8_SA(b, h) + aoff + m * 2048 + k * 1024); } while (0)
; #define PG8_LDB(dst, b, h) do { _Pragma("unroll") for (int n = 0; n < 2; ++n) _Pragma("unroll") for (int k = 0; k < 2; ++k) dst[n][k] = *(const LAS bf16x8*)(lds + PG8_SB(b, h) + boff + n * 2048 + k * 1024); } while (0)
; #define PG8_MMA(ai, bj, At, Bt) do { __builtin_amdgcn_s_setprio(1); _Pragma("unroll") for (int m = 0; m < 4; ++m) _Pragma("unroll") for (int n = 0; n < 2; ++n) _Pragma("unroll") for (int k = 0; k < 2; ++k) \
;         acc[ai][bj][m][n] = __builtin_amdgcn_mfma_f32_16x16x32_bf16(Bt[n][k], At[m][k], acc[ai][bj][m][n], 0, 0, 0); __builtin_amdgcn_s_setprio(0); } while (0)
; #define PG8_WAIT_V(n) asm volatile("s_waitcnt vmcnt(" #n ")" ::: "memory")
; #define PG8_WAIT_L(n) asm volatile("s_waitcnt lgkmcnt(" #n ")" ::: "memory")
; #define PG8_BAR __builtin_amdgcn_s_barrier()
; #define PG8_SCHED __builtin_amdgcn_sched_barrier(0)
; template <class Epi, class Sched, bool ALIGN_EPI = true>
; __device__ __forceinline__ void gemm_phase(LAS unsigned char* lds, const Gemm g, const Sched& S, const Epi& E) {
;     ...
;             PG8_WAIT_V(8); PG8_WAIT_L(0); PG8_BAR; PG8_MMA(1, 0, At, B0); PG8_MMA(1, 1, At, B1); PG8_BAR; PG8_SCHED;
;             PG8_LDB(B0, 1, 0); PG8_LDB(B1, 1, 1); PG8_SCHED; PG8_LDA(At, 1, 0); PG8_STAGE(PG8_SA(0, 1), a2 + hA, voffA);
;             PG8_WAIT_V(8); PG8_WAIT_L(0); PG8_BAR; PG8_MMA(0, 0, At, B0); PG8_MMA(0, 1, At, B1); PG8_BAR; PG8_SCHED;
	v_mfma_f32_16x16x32_bf16 v[4:7], v[174:177], v[214:217], v[4:7]
	v_mfma_f32_16x16x32_bf16 v[4:7], v[178:181], v[218:221], v[4:7]
	s_setprio 0
	s_add_i32 s30, 0, 0x18000
	v_add_u32_e32 v2, s30, v204
	s_add_i32 s31, 0, 0x1c000
	ds_read_b128 v[132:135], v2
	ds_read_b128 v[136:139], v2 offset:1024
	ds_read_b128 v[140:143], v2 offset:2048
	ds_read_b128 v[144:147], v2 offset:3072
	v_add_u32_e32 v2, s31, v204
	ds_read_b128 v[148:151], v2
	ds_read_b128 v[152:155], v2 offset:1024
	ds_read_b128 v[174:177], v2 offset:2048
	ds_read_b128 v[178:181], v2 offset:3072
	s_add_u32 s26, s58, 0x80000
	s_addc_u32 s27, s59, 0
	s_mov_b32 m0, s64
	v_lshl_add_u64 v[224:225], s[26:27], 0, v[168:169]
	ds_read_b128 v[182:185], v205 offset:32768
	ds_read_b128 v[186:189], v205 offset:33792
	ds_read_b128 v[190:193], v205 offset:34816
	ds_read_b128 v[194:197], v205 offset:35840
	ds_read_b128 v[206:209], v205 offset:36864
	ds_read_b128 v[210:213], v205 offset:37888
	ds_read_b128 v[214:217], v205 offset:38912
	ds_read_b128 v[218:221], v205 offset:39936
	global_load_lds_dwordx4 v[224:225], off
	v_lshl_add_u64 v[224:225], s[26:27], 0, v[164:165]
	s_mov_b32 m0, s65
	s_nop 0
	global_load_lds_dwordx4 v[224:225], off
	s_waitcnt vmcnt(8)
	s_waitcnt lgkmcnt(0)
	s_barrier
	s_setprio 1
	s_waitcnt lgkmcnt(0)
	v_mfma_f32_16x16x32_bf16 v[116:119], v[132:135], v[182:185], v[116:119]
	v_mfma_f32_16x16x32_bf16 v[116:119], v[136:139], v[186:189], v[116:119]
	v_mfma_f32_16x16x32_bf16 v[100:103], v[140:143], v[182:185], v[100:103]
	v_mfma_f32_16x16x32_bf16 v[100:103], v[144:147], v[186:189], v[100:103]
	v_mfma_f32_16x16x32_bf16 v[108:111], v[132:135], v[190:193], v[108:111]
	v_mfma_f32_16x16x32_bf16 v[108:111], v[136:139], v[194:197], v[108:111]
	v_mfma_f32_16x16x32_bf16 v[96:99], v[140:143], v[190:193], v[96:99]
	v_mfma_f32_16x16x32_bf16 v[96:99], v[144:147], v[194:197], v[96:99]
	v_mfma_f32_16x16x32_bf16 v[88:91], v[132:135], v[206:209], v[88:91]
	v_mfma_f32_16x16x32_bf16 v[88:91], v[136:139], v[210:213], v[88:91]
	v_mfma_f32_16x16x32_bf16 v[84:87], v[140:143], v[206:209], v[84:87]
	v_mfma_f32_16x16x32_bf16 v[84:87], v[144:147], v[210:213], v[84:87]
	v_mfma_f32_16x16x32_bf16 v[72:75], v[132:135], v[214:217], v[72:75]
	v_mfma_f32_16x16x32_bf16 v[72:75], v[136:139], v[218:221], v[72:75]
	v_mfma_f32_16x16x32_bf16 v[80:83], v[140:143], v[214:217], v[80:83]
	v_mfma_f32_16x16x32_bf16 v[80:83], v[144:147], v[218:221], v[80:83]
	s_setprio 0
	s_setprio 1
	v_mfma_f32_16x16x32_bf16 v[128:131], v[148:151], v[182:185], v[128:131]
	v_mfma_f32_16x16x32_bf16 v[128:131], v[152:155], v[186:189], v[128:131]
	v_mfma_f32_16x16x32_bf16 v[44:47], v[174:177], v[182:185], v[44:47]
	v_mfma_f32_16x16x32_bf16 v[44:47], v[178:181], v[186:189], v[44:47]
	v_mfma_f32_16x16x32_bf16 v[124:127], v[148:151], v[190:193], v[124:127]
	v_mfma_f32_16x16x32_bf16 v[124:127], v[152:155], v[194:197], v[124:127]
	v_mfma_f32_16x16x32_bf16 v[36:39], v[174:177], v[190:193], v[36:39]
	v_mfma_f32_16x16x32_bf16 v[36:39], v[178:181], v[194:197], v[36:39]
	v_mfma_f32_16x16x32_bf16 v[120:123], v[148:151], v[206:209], v[120:123]
	v_mfma_f32_16x16x32_bf16 v[120:123], v[152:155], v[210:213], v[120:123]
	v_mfma_f32_16x16x32_bf16 v[32:35], v[174:177], v[206:209], v[32:35]
	v_mfma_f32_16x16x32_bf16 v[32:35], v[178:181], v[210:213], v[32:35]
	v_mfma_f32_16x16x32_bf16 v[112:115], v[148:151], v[214:217], v[112:115]
	v_mfma_f32_16x16x32_bf16 v[112:115], v[152:155], v[218:221], v[112:115]
	s_setprio 2
	s_barrier
; #define PG8_STAGE(bufoff, gbase, voff) do { _Pragma("unroll") for (int _i = 0; _i < 2; ++_i) \
;         __builtin_amdgcn_global_load_lds((const unsigned*)((const char*)(gbase) + (voff)[_i]), (LAS unsigned*)(lds + (bufoff) + ldsw + _i * 8192), 16, 0, 0); } while (0)
; #define PG8_LDA(dst, b, h) do { _Pragma("unroll") for (int m = 0; m < 4; ++m) _Pragma("unroll") for (int k = 0; k < 2; ++k) dst[m][k] = *(const LAS bf16x8*)(lds + PG8_SA(b, h) + aoff + m * 2048 + k * 1024); } while (0)
; #define PG8_MMA(ai, bj, At, Bt) do { __builtin_amdgcn_s_setprio(1); _Pragma("unroll") for (int m = 0; m < 4; ++m) _Pragma("unroll") for (int n = 0; n < 2; ++n) _Pragma("unroll") for (int k = 0; k < 2; ++k) \
;         acc[ai][bj][m][n] = __builtin_amdgcn_mfma_f32_16x16x32_bf16(Bt[n][k], At[m][k], acc[ai][bj][m][n], 0, 0, 0); __builtin_amdgcn_s_setprio(0); } while (0)
; #define PG8_WAIT_V(n) asm volatile("s_waitcnt vmcnt(" #n ")" ::: "memory")
; #define PG8_WAIT_L(n) asm volatile("s_waitcnt lgkmcnt(" #n ")" ::: "memory")
; #define PG8_BAR __builtin_amdgcn_s_barrier()
; #define PG8_SCHED __builtin_amdgcn_sched_barrier(0)
; template <class Epi, class Sched, bool ALIGN_EPI = true>
; __device__ __forceinline__ void gemm_phase(LAS unsigned char* lds, const Gemm g, const Sched& S, const Epi& E) {
;     ...
;             const bool last = (t == nt - 2);
;             const char* a1 = cA + (size_t)(t + 1) * kstep;
;             const char* a2 = last ? nA : cA + (size_t)(t + 2) * kstep; const char* b2 = last ? nB : cB + (size_t)(t + 2) * kstep;
;             const char* a3 = a2 + kstep; const char* b3 = b2 + kstep;
;     ...
;             PG8_WAIT_V(8); PG8_WAIT_L(0); PG8_BAR; PG8_MMA(0, 0, At, B0); PG8_MMA(0, 1, At, B1); PG8_BAR; PG8_SCHED;
;             PG8_LDA(At, 1, 1); PG8_STAGE(PG8_SB(1, 0), b3, voffB); PG8_STAGE(PG8_SB(1, 1), b3 + hB, voffB); PG8_STAGE(PG8_SA(1, 0), a3, voffA);
;             PG8_WAIT_V(8); PG8_WAIT_L(0); PG8_BAR; PG8_MMA(1, 0, At, B0); PG8_MMA(1, 1, At, B1); PG8_BAR; PG8_SCHED;
	v_mfma_f32_16x16x32_bf16 v[28:31], v[174:177], v[214:217], v[28:31]
	v_mfma_f32_16x16x32_bf16 v[28:31], v[178:181], v[218:221], v[28:31]
	s_setprio 0
	s_add_i32 s26, s30, s61
	v_lshl_add_u64 v[156:157], v[156:157], 0, s[86:87]
	s_mov_b32 m0, s26
	ds_read_b128 v[182:185], v205 offset:49152
	ds_read_b128 v[186:189], v205 offset:50176
	ds_read_b128 v[190:193], v205 offset:51200
	ds_read_b128 v[194:197], v205 offset:52224
	ds_read_b128 v[206:209], v205 offset:53248
	ds_read_b128 v[210:213], v205 offset:54272
	ds_read_b128 v[214:217], v205 offset:55296
	ds_read_b128 v[218:221], v205 offset:56320
	global_load_lds_dwordx4 v[156:157], off
	s_add_i32 m0, s26, 0x2000
	s_add_u32 s26, s44, 0x80080
	v_lshl_add_u64 v[156:157], v[160:161], 0, s[86:87]
	s_addc_u32 s27, s45, 0
	s_add_i32 s30, s31, s61
	global_load_lds_dwordx4 v[156:157], off
	v_lshl_add_u64 v[156:157], s[26:27], 0, v[166:167]
	s_mov_b32 m0, s30
	s_nop 0
	global_load_lds_dwordx4 v[156:157], off
	v_lshl_add_u64 v[156:157], s[26:27], 0, v[0:1]
	s_add_i32 m0, s30, 0x2000
	s_nop 0
	global_load_lds_dwordx4 v[156:157], off
	v_lshl_add_u64 v[156:157], v[162:163], 0, s[86:87]
	s_mov_b32 m0, s75
	s_nop 0
	global_load_lds_dwordx4 v[156:157], off
	v_lshl_add_u64 v[156:157], v[222:223], 0, s[86:87]
	s_mov_b32 m0, s76
	s_nop 0
	global_load_lds_dwordx4 v[156:157], off
	s_waitcnt vmcnt(8)
	s_waitcnt lgkmcnt(0)
	s_barrier
	s_setprio 1
	s_waitcnt lgkmcnt(0)
	v_mfma_f32_16x16x32_bf16 v[60:63], v[132:135], v[182:185], v[60:63]
	v_mfma_f32_16x16x32_bf16 v[60:63], v[136:139], v[186:189], v[60:63]
	s_add_i32 s25, s25, 2
	s_add_u32 s6, s6, 0x100
	v_mfma_f32_16x16x32_bf16 v[68:71], v[140:143], v[182:185], v[68:71]
	v_mfma_f32_16x16x32_bf16 v[68:71], v[144:147], v[186:189], v[68:71]
	s_addc_u32 s7, s7, 0
	s_add_u32 s19, s19, 0x100
	v_mfma_f32_16x16x32_bf16 v[40:43], v[132:135], v[190:193], v[40:43]
	v_mfma_f32_16x16x32_bf16 v[40:43], v[136:139], v[194:197], v[40:43]
	s_addc_u32 s24, s24, 0
	s_add_u32 s26, s6, 0xfff80080
	v_mfma_f32_16x16x32_bf16 v[64:67], v[140:143], v[190:193], v[64:67]
	v_mfma_f32_16x16x32_bf16 v[64:67], v[144:147], v[194:197], v[64:67]
	s_addc_u32 s27, s7, -1
	s_add_i32 s30, 0, 0x10000
	v_mfma_f32_16x16x32_bf16 v[24:27], v[132:135], v[206:209], v[24:27]
	v_mfma_f32_16x16x32_bf16 v[24:27], v[136:139], v[210:213], v[24:27]
	s_cmp_eq_u32 s25, 28
	s_cselect_b32 s59, s16, s27
	v_mfma_f32_16x16x32_bf16 v[56:59], v[140:143], v[206:209], v[56:59]
	v_mfma_f32_16x16x32_bf16 v[56:59], v[144:147], v[210:213], v[56:59]
	s_cselect_b32 s58, s17, s26
	s_cselect_b32 s45, s15, s24
	v_mfma_f32_16x16x32_bf16 v[12:15], v[132:135], v[214:217], v[12:15]
	v_mfma_f32_16x16x32_bf16 v[12:15], v[136:139], v[218:221], v[12:15]
	s_cselect_b32 s44, s18, s19
	s_add_i32 s31, 0, 0x14000
	v_mfma_f32_16x16x32_bf16 v[48:51], v[140:143], v[214:217], v[48:51]
	v_mfma_f32_16x16x32_bf16 v[48:51], v[144:147], v[218:221], v[48:51]
	s_setprio 0
	s_setprio 1
	v_mfma_f32_16x16x32_bf16 v[104:107], v[148:151], v[182:185], v[104:107]
	v_mfma_f32_16x16x32_bf16 v[104:107], v[152:155], v[186:189], v[104:107]
	v_mfma_f32_16x16x32_bf16 v[20:23], v[174:177], v[182:185], v[20:23]
	v_mfma_f32_16x16x32_bf16 v[20:23], v[178:181], v[186:189], v[20:23]
	v_mfma_f32_16x16x32_bf16 v[92:95], v[148:151], v[190:193], v[92:95]
	v_mfma_f32_16x16x32_bf16 v[92:95], v[152:155], v[194:197], v[92:95]
	v_mfma_f32_16x16x32_bf16 v[16:19], v[174:177], v[190:193], v[16:19]
	v_mfma_f32_16x16x32_bf16 v[16:19], v[178:181], v[194:197], v[16:19]
	v_mfma_f32_16x16x32_bf16 v[76:79], v[148:151], v[206:209], v[76:79]
	v_mfma_f32_16x16x32_bf16 v[76:79], v[152:155], v[210:213], v[76:79]
	v_mfma_f32_16x16x32_bf16 v[8:11], v[174:177], v[206:209], v[8:11]
	v_mfma_f32_16x16x32_bf16 v[8:11], v[178:181], v[210:213], v[8:11]
	v_mfma_f32_16x16x32_bf16 v[52:55], v[148:151], v[214:217], v[52:55]
	v_mfma_f32_16x16x32_bf16 v[52:55], v[152:155], v[218:221], v[52:55]
	s_setprio 2
	s_barrier
	v_mfma_f32_16x16x32_bf16 v[4:7], v[174:177], v[214:217], v[4:7]
	v_mfma_f32_16x16x32_bf16 v[4:7], v[178:181], v[218:221], v[4:7]
	s_setprio 0
	s_cmp_gt_u32 s25, 29
	s_cbranch_scc0 .LBB0_828
